# EpiRes v2 (LDS-transposed coalesced loads, sc1 stores) + EpiConv DPP zero-init removal + G1 epilogue LDS-transposed stores + 2-deep pooling loop
# speedup vs baseline: 1.0296x; 1.0100x over previous
; __device__ __forceinline__ unsigned cvt_pk_bf16(float lo, float hi) { unsigned r; asm volatile("v_cvt_pk_bf16_f32 %0, %1, %2" : "=v"(r) : "v"(lo), "v"(hi)); return r; }
; #define PG8_BAR __builtin_amdgcn_s_barrier()
;     __device__ __forceinline__ void operator()(const f32x4 (&acc)[2][2][4][2], const Unit& u, int wr, int wc, int fr, int fq) const {
;         const int row0 = u.pm * BM + wr * 64 + fr; const int col0 = u.pn * BM + wc * 32 + 8 * fq;
; #pragma unroll
;         for (int ai = 0; ai < 2; ++ai)
; #pragma unroll
;             for (int m = 0; m < 4; ++m) { bf16_t* rowp = O + (size_t)(row0 + ai * HALF + m * 16) * ldc + col0;
; #pragma unroll
;                 for (int bj = 0; bj < 2; ++bj) { const f32x4 v0 = acc[ai][bj][m][0], v1 = acc[ai][bj][m][1];
;                     u32x4 w; w.x = cvt_pk_bf16(v0[0], v0[1]); w.y = cvt_pk_bf16(v0[2], v0[3]); w.z = cvt_pk_bf16(v1[0], v1[1]); w.w = cvt_pk_bf16(v1[2], v1[3]);
;                     *(u32x4*)(rowp + bj * HALF) = w; } }
; template <class Epi, class Sched, bool ALIGN_EPI = false, bool SP2 = false>
; __device__ __forceinline__ void gemm_phase(PG8_LAS unsigned char* lds, const Gemm g, const Sched& S, const Epi& E) {
;     ...
;         if (!has_next) break;
; #pragma unroll
;         for (int a = 0; a < 2; ++a)
; #pragma unroll
;             for (int b = 0; b < 2; ++b)
; #pragma unroll
;                 for (int m = 0; m < 4; ++m)
; #pragma unroll
;                     for (int n = 0; n < 2; ++n) acc[a][b][m][n] = (f32x4){0.f, 0.f, 0.f, 0.f};
;         cur = nxt; cA = nA; cB = nB; ++ui;
;         if constexpr (ALIGN_EPI) { if (wr == 1) PG8_BAR; }
.LBB0_188:
	v_mbcnt_lo_u32_b32 v186, -1, 0
	v_mbcnt_hi_u32_b32 v186, -1, v186
	v_and_b32_e32 v189, 64, v150
	v_and_b32_e32 v190, 0x60, v152
	v_lshrrev_b32_e32 v187, 2, v186
	v_and_b32_e32 v188, 3, v186
	v_mul_u32_u24_e32 v193, 0xc0, v189
	v_mul_u32_u24_e32 v191, 0x60, v190
	v_add_u32_e32 v193, v193, v191
	v_add_u32_e32 v193, 0x20000, v193
	v_and_b32_e32 v191, 15, v186
	v_mul_u32_u24_e32 v191, 0x90, v191
	v_lshrrev_b32_e32 v192, 4, v186
	v_lshl_add_u32 v191, v192, 4, v191
	v_add_u32_e32 v194, v193, v191
	v_mul_u32_u24_e32 v191, 0x90, v187
	v_lshl_add_u32 v191, v188, 4, v191
	v_add_u32_e32 v195, v193, v191
	v_add_u32_e32 v191, v189, v187
	v_lshl_add_u32 v191, s35, 8, v191
	v_lshl_add_u32 v192, v188, 3, v190
	v_lshl_or_b32 v192, s34, 8, v192
	v_mul_u32_u24_e32 v191, 0x1200, v191
	v_lshl_add_u32 v196, v192, 1, v191
	v_add_u32_e32 v197, 0x12000, v196
	v_add_u32_e32 v198, 0x24000, v196
	v_add_u32_e32 v199, 0x36000, v196
	v_add_u32_e32 v200, 0x90000, v196
	v_add_u32_e32 v201, 0xa2000, v196
	v_add_u32_e32 v202, 0xb4000, v196
	v_add_u32_e32 v203, 0xc6000, v196
	v_cvt_pk_bf16_f32 v134, v134, v135
	v_cvt_pk_bf16_f32 v135, v136, v137
	v_cvt_pk_bf16_f32 v136, v130, v131
	v_cvt_pk_bf16_f32 v137, v132, v133
	ds_write_b128 v194, v[134:137]
	ds_read_b128 v[134:137], v195
	v_cvt_pk_bf16_f32 v122, v122, v123
	v_cvt_pk_bf16_f32 v123, v124, v125
	v_cvt_pk_bf16_f32 v124, v114, v115
	v_cvt_pk_bf16_f32 v125, v116, v117
	ds_write_b128 v194, v[122:125]
	ds_read_b128 v[122:125], v195
	s_waitcnt lgkmcnt(2)
	global_store_dwordx4 v196, v[134:137], s[92:93]
	v_cvt_pk_bf16_f32 v114, v126, v127
	v_cvt_pk_bf16_f32 v115, v128, v129
	v_cvt_pk_bf16_f32 v116, v118, v119
	v_cvt_pk_bf16_f32 v117, v120, v121
	ds_write_b128 v194, v[114:117]
	ds_read_b128 v[114:117], v195
	s_waitcnt lgkmcnt(2)
	global_store_dwordx4 v196, v[122:125], s[92:93] offset:256
	v_cvt_pk_bf16_f32 v106, v106, v107
	v_cvt_pk_bf16_f32 v107, v108, v109
	v_cvt_pk_bf16_f32 v108, v98, v99
	v_cvt_pk_bf16_f32 v109, v100, v101
	ds_write_b128 v194, v[106:109]
	ds_read_b128 v[106:109], v195
	s_waitcnt lgkmcnt(2)
	global_store_dwordx4 v197, v[114:117], s[92:93]
	v_cvt_pk_bf16_f32 v98, v110, v111
	v_cvt_pk_bf16_f32 v99, v112, v113
	v_cvt_pk_bf16_f32 v100, v102, v103
	v_cvt_pk_bf16_f32 v101, v104, v105
	ds_write_b128 v194, v[98:101]
	ds_read_b128 v[98:101], v195
	s_waitcnt lgkmcnt(2)
	global_store_dwordx4 v197, v[106:109], s[92:93] offset:256
	v_cvt_pk_bf16_f32 v90, v90, v91
	v_cvt_pk_bf16_f32 v91, v92, v93
	v_cvt_pk_bf16_f32 v92, v82, v83
	v_cvt_pk_bf16_f32 v93, v84, v85
	ds_write_b128 v194, v[90:93]
	ds_read_b128 v[90:93], v195
	s_waitcnt lgkmcnt(2)
	global_store_dwordx4 v198, v[98:101], s[92:93]
	v_cvt_pk_bf16_f32 v82, v94, v95
	v_cvt_pk_bf16_f32 v83, v96, v97
	v_cvt_pk_bf16_f32 v84, v86, v87
	v_cvt_pk_bf16_f32 v85, v88, v89
	ds_write_b128 v194, v[82:85]
	ds_read_b128 v[82:85], v195
	s_waitcnt lgkmcnt(2)
	global_store_dwordx4 v198, v[90:93], s[92:93] offset:256
	v_cvt_pk_bf16_f32 v78, v78, v79
	v_cvt_pk_bf16_f32 v79, v80, v81
	v_cvt_pk_bf16_f32 v80, v74, v75
	v_cvt_pk_bf16_f32 v81, v76, v77
	ds_write_b128 v194, v[78:81]
	ds_read_b128 v[78:81], v195
	s_waitcnt lgkmcnt(2)
	global_store_dwordx4 v199, v[82:85], s[92:93]
	v_cvt_pk_bf16_f32 v70, v70, v71
	v_cvt_pk_bf16_f32 v71, v72, v73
	v_cvt_pk_bf16_f32 v72, v66, v67
	v_cvt_pk_bf16_f32 v73, v68, v69
	ds_write_b128 v194, v[70:73]
	ds_read_b128 v[70:73], v195
	s_waitcnt lgkmcnt(2)
	global_store_dwordx4 v199, v[78:81], s[92:93] offset:256
	v_cvt_pk_bf16_f32 v58, v58, v59
	v_cvt_pk_bf16_f32 v59, v60, v61
	v_cvt_pk_bf16_f32 v60, v50, v51
	v_cvt_pk_bf16_f32 v61, v52, v53
	ds_write_b128 v194, v[58:61]
	ds_read_b128 v[58:61], v195
	s_waitcnt lgkmcnt(2)
	global_store_dwordx4 v200, v[70:73], s[92:93]
	v_cvt_pk_bf16_f32 v50, v62, v63
	v_cvt_pk_bf16_f32 v51, v64, v65
	v_cvt_pk_bf16_f32 v52, v54, v55
	v_cvt_pk_bf16_f32 v53, v56, v57
	ds_write_b128 v194, v[50:53]
	ds_read_b128 v[50:53], v195
	s_waitcnt lgkmcnt(2)
	global_store_dwordx4 v200, v[58:61], s[92:93] offset:256
	v_cvt_pk_bf16_f32 v42, v42, v43
	v_cvt_pk_bf16_f32 v43, v44, v45
	v_cvt_pk_bf16_f32 v44, v26, v27
	v_cvt_pk_bf16_f32 v45, v28, v29
	ds_write_b128 v194, v[42:45]
	ds_read_b128 v[42:45], v195
	s_waitcnt lgkmcnt(2)
	global_store_dwordx4 v201, v[50:53], s[92:93]
	v_cvt_pk_bf16_f32 v26, v46, v47
	v_cvt_pk_bf16_f32 v27, v48, v49
	v_cvt_pk_bf16_f32 v28, v30, v31
	v_cvt_pk_bf16_f32 v29, v32, v33
	ds_write_b128 v194, v[26:29]
	ds_read_b128 v[26:29], v195
	s_waitcnt lgkmcnt(2)
	global_store_dwordx4 v201, v[42:45], s[92:93] offset:256
	v_cvt_pk_bf16_f32 v18, v18, v19
	v_cvt_pk_bf16_f32 v19, v20, v21
	v_cvt_pk_bf16_f32 v20, v10, v11
	v_cvt_pk_bf16_f32 v21, v12, v13
	ds_write_b128 v194, v[18:21]
	ds_read_b128 v[18:21], v195
	s_waitcnt lgkmcnt(2)
	global_store_dwordx4 v202, v[26:29], s[92:93]
	v_cvt_pk_bf16_f32 v10, v22, v23
	v_cvt_pk_bf16_f32 v11, v24, v25
	v_cvt_pk_bf16_f32 v12, v14, v15
	v_cvt_pk_bf16_f32 v13, v16, v17
	ds_write_b128 v194, v[10:13]
	ds_read_b128 v[10:13], v195
	s_waitcnt lgkmcnt(2)
	global_store_dwordx4 v202, v[18:21], s[92:93] offset:256
	v_cvt_pk_bf16_f32 v6, v6, v7
	v_cvt_pk_bf16_f32 v7, v8, v9
	v_cvt_pk_bf16_f32 v8, v2, v3
	v_cvt_pk_bf16_f32 v9, v4, v5
	ds_write_b128 v194, v[6:9]
	ds_read_b128 v[6:9], v195
	s_waitcnt lgkmcnt(2)
	global_store_dwordx4 v203, v[10:13], s[92:93]
	s_waitcnt lgkmcnt(0)
	global_store_dwordx4 v203, v[6:9], s[92:93] offset:256
	s_andn2_b64 vcc, exec, s[0:1]
	s_mov_b64 s[0:1], -1
	s_cbranch_vccnz .LBB0_177
	s_andn2_b64 vcc, exec, s[2:3]
	s_cbranch_vccnz .LBB0_176
	s_barrier
	s_branch .LBB0_176

; __device__ __forceinline__ float lo16(unsigned w) { return __uint_as_float(w << 16); }
; __device__ __forceinline__ float hi16(unsigned w) { return __uint_as_float(w & 0xffff0000u); }
; __device__ __forceinline__ void prep_pool_item(const KPD& kp, int l, int sc, unsigned char* lds, int tid, int lane, int wave) {
;     ...
;       for (int j = lo; j < hi; ++j) { const bf16* up = P + (size_t)(rowbase + j - s0) * INP + cb;
; #pragma unroll
;           for (int q = 0; q < 4; ++q) { const v4u v = *(const v4u*)(up + 8 * q);
;               acc[8 * q] += lo16(v.x); acc[8 * q + 1] += hi16(v.x); acc[8 * q + 2] += lo16(v.y); acc[8 * q + 3] += hi16(v.y); acc[8 * q + 4] += lo16(v.z); acc[8 * q + 5] += hi16(v.z); acc[8 * q + 6] += lo16(v.w); acc[8 * q + 7] += hi16(v.w); } }
.LBB0_298:
	s_mov_b64 s[2:3], exec
	v_mov_b32_e32 v157, 0
	v_mov_b32_e32 v158, 0x1200
	global_load_dwordx4 v[62:65], v[58:59], off
	global_load_dwordx4 v[66:69], v[58:59], off offset:-16
	global_load_dwordx4 v[96:99], v[58:59], off offset:-32
	global_load_dwordx4 v[100:103], v[58:59], off offset:-48
.Lpool_loop:
	v_add_u32_e32 v61, 1, v61
	v_cmp_lt_i32_e32 vcc, v61, v60
	s_and_b64 vcc, exec, vcc
	s_cbranch_scc0 .Lpool_tailA
	v_cndmask_b32_e32 v156, v157, v158, vcc
	v_lshl_add_u64 v[58:59], v[58:59], 0, v[156:157]
	global_load_dwordx4 v[106:109], v[58:59], off
	global_load_dwordx4 v[110:113], v[58:59], off offset:-16
	global_load_dwordx4 v[114:117], v[58:59], off offset:-32
	global_load_dwordx4 v[150:153], v[58:59], off offset:-48
	s_waitcnt vmcnt(4)
	v_and_b32_e32 v104, 0xffff0000, v100
	v_lshlrev_b32_e32 v105, 16, v100
	v_and_b32_e32 v100, 0xffff0000, v101
	v_lshlrev_b32_e32 v101, 16, v101
	v_pk_add_f32 v[54:55], v[54:55], v[100:101]
	v_and_b32_e32 v100, 0xffff0000, v102
	v_lshlrev_b32_e32 v101, 16, v102
	v_pk_add_f32 v[52:53], v[52:53], v[100:101]
	v_and_b32_e32 v100, 0xffff0000, v103
	v_lshlrev_b32_e32 v101, 16, v103
	v_pk_add_f32 v[50:51], v[50:51], v[100:101]
	v_and_b32_e32 v100, 0xffff0000, v96
	v_lshlrev_b32_e32 v101, 16, v96
	v_and_b32_e32 v96, 0xffff0000, v97
	v_lshlrev_b32_e32 v97, 16, v97
	v_pk_add_f32 v[46:47], v[46:47], v[96:97]
	v_and_b32_e32 v96, 0xffff0000, v98
	v_lshlrev_b32_e32 v97, 16, v98
	v_pk_add_f32 v[44:45], v[44:45], v[96:97]
	v_and_b32_e32 v96, 0xffff0000, v99
	v_lshlrev_b32_e32 v97, 16, v99
	v_pk_add_f32 v[42:43], v[42:43], v[96:97]
	v_and_b32_e32 v96, 0xffff0000, v66
	v_lshlrev_b32_e32 v97, 16, v66
	v_and_b32_e32 v66, 0xffff0000, v67
	v_lshlrev_b32_e32 v67, 16, v67
	v_pk_add_f32 v[14:15], v[14:15], v[66:67]
	v_and_b32_e32 v66, 0xffff0000, v68
	v_lshlrev_b32_e32 v67, 16, v68
	v_pk_add_f32 v[12:13], v[12:13], v[66:67]
	v_and_b32_e32 v66, 0xffff0000, v69
	v_lshlrev_b32_e32 v67, 16, v69
	v_pk_add_f32 v[10:11], v[10:11], v[66:67]
	v_and_b32_e32 v66, 0xffff0000, v62
	v_lshlrev_b32_e32 v67, 16, v62
	v_and_b32_e32 v62, 0xffff0000, v63
	v_lshlrev_b32_e32 v63, 16, v63
	v_pk_add_f32 v[6:7], v[6:7], v[62:63]
	v_and_b32_e32 v62, 0xffff0000, v64
	v_lshlrev_b32_e32 v63, 16, v64
	v_pk_add_f32 v[4:5], v[4:5], v[62:63]
	v_and_b32_e32 v62, 0xffff0000, v65
	v_lshlrev_b32_e32 v63, 16, v65
	v_pk_add_f32 v[56:57], v[56:57], v[104:105]
	v_pk_add_f32 v[48:49], v[48:49], v[100:101]
	v_pk_add_f32 v[16:17], v[16:17], v[96:97]
	v_pk_add_f32 v[8:9], v[8:9], v[66:67]
	v_pk_add_f32 v[2:3], v[2:3], v[62:63]
	s_mov_b64 exec, vcc
	v_add_u32_e32 v61, 1, v61
	v_cmp_lt_i32_e32 vcc, v61, v60
	s_and_b64 vcc, exec, vcc
	s_cbranch_scc0 .Lpool_tailB
	v_cndmask_b32_e32 v156, v157, v158, vcc
	v_lshl_add_u64 v[58:59], v[58:59], 0, v[156:157]
	global_load_dwordx4 v[62:65], v[58:59], off
	global_load_dwordx4 v[66:69], v[58:59], off offset:-16
	global_load_dwordx4 v[96:99], v[58:59], off offset:-32
	global_load_dwordx4 v[100:103], v[58:59], off offset:-48
	s_waitcnt vmcnt(4)
	v_and_b32_e32 v154, 0xffff0000, v150
	v_lshlrev_b32_e32 v155, 16, v150
	v_and_b32_e32 v150, 0xffff0000, v151
	v_lshlrev_b32_e32 v151, 16, v151
	v_pk_add_f32 v[54:55], v[54:55], v[150:151]
	v_and_b32_e32 v150, 0xffff0000, v152
	v_lshlrev_b32_e32 v151, 16, v152
	v_pk_add_f32 v[52:53], v[52:53], v[150:151]
	v_and_b32_e32 v150, 0xffff0000, v153
	v_lshlrev_b32_e32 v151, 16, v153
	v_pk_add_f32 v[50:51], v[50:51], v[150:151]
	v_and_b32_e32 v150, 0xffff0000, v114
	v_lshlrev_b32_e32 v151, 16, v114
	v_and_b32_e32 v114, 0xffff0000, v115
	v_lshlrev_b32_e32 v115, 16, v115
	v_pk_add_f32 v[46:47], v[46:47], v[114:115]
	v_and_b32_e32 v114, 0xffff0000, v116
	v_lshlrev_b32_e32 v115, 16, v116
	v_pk_add_f32 v[44:45], v[44:45], v[114:115]
	v_and_b32_e32 v114, 0xffff0000, v117
	v_lshlrev_b32_e32 v115, 16, v117
	v_pk_add_f32 v[42:43], v[42:43], v[114:115]
	v_and_b32_e32 v114, 0xffff0000, v110
	v_lshlrev_b32_e32 v115, 16, v110
	v_and_b32_e32 v110, 0xffff0000, v111
	v_lshlrev_b32_e32 v111, 16, v111
	v_pk_add_f32 v[14:15], v[14:15], v[110:111]
	v_and_b32_e32 v110, 0xffff0000, v112
	v_lshlrev_b32_e32 v111, 16, v112
	v_pk_add_f32 v[12:13], v[12:13], v[110:111]
	v_and_b32_e32 v110, 0xffff0000, v113
	v_lshlrev_b32_e32 v111, 16, v113
	v_pk_add_f32 v[10:11], v[10:11], v[110:111]
	v_and_b32_e32 v110, 0xffff0000, v106
	v_lshlrev_b32_e32 v111, 16, v106
	v_and_b32_e32 v106, 0xffff0000, v107
	v_lshlrev_b32_e32 v107, 16, v107
	v_pk_add_f32 v[6:7], v[6:7], v[106:107]
	v_and_b32_e32 v106, 0xffff0000, v108
	v_lshlrev_b32_e32 v107, 16, v108
	v_pk_add_f32 v[4:5], v[4:5], v[106:107]
	v_and_b32_e32 v106, 0xffff0000, v109
	v_lshlrev_b32_e32 v107, 16, v109
	v_pk_add_f32 v[56:57], v[56:57], v[154:155]
	v_pk_add_f32 v[48:49], v[48:49], v[150:151]
	v_pk_add_f32 v[16:17], v[16:17], v[114:115]
	v_pk_add_f32 v[8:9], v[8:9], v[110:111]
	v_pk_add_f32 v[2:3], v[2:3], v[106:107]
	s_mov_b64 exec, vcc
	s_branch .Lpool_loop
; __device__ __forceinline__ float lo16(unsigned w) { return __uint_as_float(w << 16); }
; __device__ __forceinline__ float hi16(unsigned w) { return __uint_as_float(w & 0xffff0000u); }
; __device__ __forceinline__ void prep_pool_item(const KPD& kp, int l, int sc, unsigned char* lds, int tid, int lane, int wave) {
;     ...
;       for (int j = lo; j < hi; ++j) { const bf16* up = P + (size_t)(rowbase + j - s0) * INP + cb;
; #pragma unroll
;           for (int q = 0; q < 4; ++q) { const v4u v = *(const v4u*)(up + 8 * q);
;               acc[8 * q] += lo16(v.x); acc[8 * q + 1] += hi16(v.x); acc[8 * q + 2] += lo16(v.y); acc[8 * q + 3] += hi16(v.y); acc[8 * q + 4] += lo16(v.z); acc[8 * q + 5] += hi16(v.z); acc[8 * q + 6] += lo16(v.w); acc[8 * q + 7] += hi16(v.w); } }
.Lpool_tailA:
	s_waitcnt vmcnt(0)
	v_and_b32_e32 v104, 0xffff0000, v100
	v_lshlrev_b32_e32 v105, 16, v100
	v_and_b32_e32 v100, 0xffff0000, v101
	v_lshlrev_b32_e32 v101, 16, v101
	v_pk_add_f32 v[54:55], v[54:55], v[100:101]
	v_and_b32_e32 v100, 0xffff0000, v102
	v_lshlrev_b32_e32 v101, 16, v102
	v_pk_add_f32 v[52:53], v[52:53], v[100:101]
	v_and_b32_e32 v100, 0xffff0000, v103
	v_lshlrev_b32_e32 v101, 16, v103
	v_pk_add_f32 v[50:51], v[50:51], v[100:101]
	v_and_b32_e32 v100, 0xffff0000, v96
	v_lshlrev_b32_e32 v101, 16, v96
	v_and_b32_e32 v96, 0xffff0000, v97
	v_lshlrev_b32_e32 v97, 16, v97
	v_pk_add_f32 v[46:47], v[46:47], v[96:97]
	v_and_b32_e32 v96, 0xffff0000, v98
	v_lshlrev_b32_e32 v97, 16, v98
	v_pk_add_f32 v[44:45], v[44:45], v[96:97]
	v_and_b32_e32 v96, 0xffff0000, v99
	v_lshlrev_b32_e32 v97, 16, v99
	v_pk_add_f32 v[42:43], v[42:43], v[96:97]
	v_and_b32_e32 v96, 0xffff0000, v66
	v_lshlrev_b32_e32 v97, 16, v66
	v_and_b32_e32 v66, 0xffff0000, v67
	v_lshlrev_b32_e32 v67, 16, v67
	v_pk_add_f32 v[14:15], v[14:15], v[66:67]
	v_and_b32_e32 v66, 0xffff0000, v68
	v_lshlrev_b32_e32 v67, 16, v68
	v_pk_add_f32 v[12:13], v[12:13], v[66:67]
	v_and_b32_e32 v66, 0xffff0000, v69
	v_lshlrev_b32_e32 v67, 16, v69
	v_pk_add_f32 v[10:11], v[10:11], v[66:67]
	v_and_b32_e32 v66, 0xffff0000, v62
	v_lshlrev_b32_e32 v67, 16, v62
	v_and_b32_e32 v62, 0xffff0000, v63
	v_lshlrev_b32_e32 v63, 16, v63
	v_pk_add_f32 v[6:7], v[6:7], v[62:63]
	v_and_b32_e32 v62, 0xffff0000, v64
	v_lshlrev_b32_e32 v63, 16, v64
	v_pk_add_f32 v[4:5], v[4:5], v[62:63]
	v_and_b32_e32 v62, 0xffff0000, v65
	v_lshlrev_b32_e32 v63, 16, v65
	v_pk_add_f32 v[56:57], v[56:57], v[104:105]
	v_pk_add_f32 v[48:49], v[48:49], v[100:101]
	v_pk_add_f32 v[16:17], v[16:17], v[96:97]
	v_pk_add_f32 v[8:9], v[8:9], v[66:67]
	v_pk_add_f32 v[2:3], v[2:3], v[62:63]
	s_branch .Lpool_done
.Lpool_tailB:
	s_waitcnt vmcnt(0)
	v_and_b32_e32 v154, 0xffff0000, v150
	v_lshlrev_b32_e32 v155, 16, v150
	v_and_b32_e32 v150, 0xffff0000, v151
	v_lshlrev_b32_e32 v151, 16, v151
	v_pk_add_f32 v[54:55], v[54:55], v[150:151]
	v_and_b32_e32 v150, 0xffff0000, v152
	v_lshlrev_b32_e32 v151, 16, v152
	v_pk_add_f32 v[52:53], v[52:53], v[150:151]
	v_and_b32_e32 v150, 0xffff0000, v153
	v_lshlrev_b32_e32 v151, 16, v153
	v_pk_add_f32 v[50:51], v[50:51], v[150:151]
	v_and_b32_e32 v150, 0xffff0000, v114
	v_lshlrev_b32_e32 v151, 16, v114
	v_and_b32_e32 v114, 0xffff0000, v115
	v_lshlrev_b32_e32 v115, 16, v115
	v_pk_add_f32 v[46:47], v[46:47], v[114:115]
	v_and_b32_e32 v114, 0xffff0000, v116
	v_lshlrev_b32_e32 v115, 16, v116
	v_pk_add_f32 v[44:45], v[44:45], v[114:115]
	v_and_b32_e32 v114, 0xffff0000, v117
	v_lshlrev_b32_e32 v115, 16, v117
	v_pk_add_f32 v[42:43], v[42:43], v[114:115]
	v_and_b32_e32 v114, 0xffff0000, v110
	v_lshlrev_b32_e32 v115, 16, v110
	v_and_b32_e32 v110, 0xffff0000, v111
	v_lshlrev_b32_e32 v111, 16, v111
	v_pk_add_f32 v[14:15], v[14:15], v[110:111]
	v_and_b32_e32 v110, 0xffff0000, v112
	v_lshlrev_b32_e32 v111, 16, v112
	v_pk_add_f32 v[12:13], v[12:13], v[110:111]
	v_and_b32_e32 v110, 0xffff0000, v113
	v_lshlrev_b32_e32 v111, 16, v113
	v_pk_add_f32 v[10:11], v[10:11], v[110:111]
	v_and_b32_e32 v110, 0xffff0000, v106
	v_lshlrev_b32_e32 v111, 16, v106
	v_and_b32_e32 v106, 0xffff0000, v107
	v_lshlrev_b32_e32 v107, 16, v107
	v_pk_add_f32 v[6:7], v[6:7], v[106:107]
	v_and_b32_e32 v106, 0xffff0000, v108
	v_lshlrev_b32_e32 v107, 16, v108
	v_pk_add_f32 v[4:5], v[4:5], v[106:107]
	v_and_b32_e32 v106, 0xffff0000, v109
	v_lshlrev_b32_e32 v107, 16, v109
	v_pk_add_f32 v[56:57], v[56:57], v[154:155]
	v_pk_add_f32 v[48:49], v[48:49], v[150:151]
	v_pk_add_f32 v[16:17], v[16:17], v[114:115]
	v_pk_add_f32 v[8:9], v[8:9], v[110:111]
	v_pk_add_f32 v[2:3], v[2:3], v[106:107]
.Lpool_done:
	s_or_b64 exec, exec, s[2:3]
	s_branch .LBB0_255

; #define PG8_LAS __attribute__((address_space(3)))
; __device__ __forceinline__ float dpp_ror1(float v) { return __builtin_bit_cast(float, __builtin_amdgcn_update_dpp(0, __builtin_bit_cast(int, v), 0x121, 0xf, 0xf, false)); }
; __device__ __forceinline__ float dpp_ror15(float v) { return __builtin_bit_cast(float, __builtin_amdgcn_update_dpp(0, __builtin_bit_cast(int, v), 0x12F, 0xf, 0xf, false)); }
;     __device__ __forceinline__ void operator()(const f32x4 (&acc)[2][2][4][2], const Unit& u, int wr, int wc, int fr, int fq) const {
;     ...
;                     for (int bj = 0; bj < 2; ++bj) { const f32x4 cur = acc[ai][bj][m][n];
;                         f32x4 su = cur, sd = cur;
;                         if (m > 0) { if (fr == 15) su = acc[ai][bj][m > 0 ? m - 1 : 0][n]; }
;                         if (m < 3) { if (fr == 0) sd = acc[ai][bj][m < 3 ? m + 1 : 3][n]; }
;                         f32x4 up, dn;
;                         up[0] = dpp_ror1(su[0]); up[1] = dpp_ror1(su[1]); up[2] = dpp_ror1(su[2]); up[3] = dpp_ror1(su[3]);
;                         dn[0] = dpp_ror15(sd[0]); dn[1] = dpp_ror15(sd[1]); dn[2] = dpp_ror15(sd[2]); dn[3] = dpp_ror15(sd[3]);
;                         if (m == 0) { f32x4 halo = zero4; if (blk > 0) halo = *(const PG8_LAS f32x4*)(xb + (((((blk - 1) * 2 + 1) * 4 + wc) * 4 + fq) * 16 + (bj * 2 + n) * 4)); if (fr == 0) up = halo; }
.LBB0_720:
	s_or_b64 exec, exec, s[0:1]
	s_waitcnt lgkmcnt(0)
	s_barrier
	v_cndmask_b32_e64 v38, v169, v161, s[6:7]
	v_cndmask_b32_e64 v39, v168, v160, s[6:7]
	v_cndmask_b32_e64 v40, v167, v159, s[6:7]
	v_cndmask_b32_e64 v41, v166, v158, s[6:7]
	v_readlane_b32 s0, v255, 25
	v_mov_b32_dpp v180, v166 row_ror:1 row_mask:0xf bank_mask:0xf
	v_mov_b32_dpp v181, v167 row_ror:1 row_mask:0xf bank_mask:0xf
	v_mov_b32_dpp v178, v168 row_ror:1 row_mask:0xf bank_mask:0xf
	v_mov_b32_dpp v179, v169 row_ror:1 row_mask:0xf bank_mask:0xf
	v_mov_b32_dpp v174, v41 row_ror:15 row_mask:0xf bank_mask:0xf
	v_mov_b32_dpp v175, v40 row_ror:15 row_mask:0xf bank_mask:0xf
	v_mov_b32_dpp v176, v39 row_ror:15 row_mask:0xf bank_mask:0xf
	v_mov_b32_dpp v177, v38 row_ror:15 row_mask:0xf bank_mask:0xf
	s_and_b64 vcc, exec, s[74:75]
	v_add_u32_e32 v244, s0, v230
	s_cbranch_vccz .LBB0_722
	ds_read_b128 v[170:173], v244
	s_branch .LBB0_723

; #define PG8_LAS __attribute__((address_space(3)))
; __device__ __forceinline__ float dpp_ror1(float v) { return __builtin_bit_cast(float, __builtin_amdgcn_update_dpp(0, __builtin_bit_cast(int, v), 0x121, 0xf, 0xf, false)); }
; __device__ __forceinline__ float dpp_ror15(float v) { return __builtin_bit_cast(float, __builtin_amdgcn_update_dpp(0, __builtin_bit_cast(int, v), 0x12F, 0xf, 0xf, false)); }
;     __device__ __forceinline__ void operator()(const f32x4 (&acc)[2][2][4][2], const Unit& u, int wr, int wc, int fr, int fq) const {
;     ...
;                     for (int bj = 0; bj < 2; ++bj) { const f32x4 cur = acc[ai][bj][m][n];
;                         f32x4 su = cur, sd = cur;
;                         if (m > 0) { if (fr == 15) su = acc[ai][bj][m > 0 ? m - 1 : 0][n]; }
;                         if (m < 3) { if (fr == 0) sd = acc[ai][bj][m < 3 ? m + 1 : 3][n]; }
;                         f32x4 up, dn;
;                         up[0] = dpp_ror1(su[0]); up[1] = dpp_ror1(su[1]); up[2] = dpp_ror1(su[2]); up[3] = dpp_ror1(su[3]);
;                         dn[0] = dpp_ror15(sd[0]); dn[1] = dpp_ror15(sd[1]); dn[2] = dpp_ror15(sd[2]); dn[3] = dpp_ror15(sd[3]);
;                         if (m == 0) { f32x4 halo = zero4; if (blk > 0) halo = *(const PG8_LAS f32x4*)(xb + (((((blk - 1) * 2 + 1) * 4 + wc) * 4 + fq) * 16 + (bj * 2 + n) * 4)); if (fr == 0) up = halo; }
.LBB0_727:
	v_cndmask_b32_e64 v38, v165, v157, s[6:7]
	v_cndmask_b32_e64 v39, v164, v156, s[6:7]
	v_cndmask_b32_e64 v40, v163, v155, s[6:7]
	v_cndmask_b32_e64 v41, v162, v154, s[6:7]
	v_mov_b32_dpp v201, v38 row_ror:15 row_mask:0xf bank_mask:0xf
	v_cndmask_b32_e64 v38, 0, 1, s[74:75]
	v_mov_b32_dpp v245, v162 row_ror:1 row_mask:0xf bank_mask:0xf
	v_mov_b32_dpp v246, v163 row_ror:1 row_mask:0xf bank_mask:0xf
	v_mov_b32_dpp v247, v164 row_ror:1 row_mask:0xf bank_mask:0xf
	v_mov_b32_dpp v248, v165 row_ror:1 row_mask:0xf bank_mask:0xf
	v_mov_b32_dpp v202, v41 row_ror:15 row_mask:0xf bank_mask:0xf
	v_mov_b32_dpp v203, v40 row_ror:15 row_mask:0xf bank_mask:0xf
	v_mov_b32_dpp v200, v39 row_ror:15 row_mask:0xf bank_mask:0xf
	v_cmp_ne_u32_e64 s[52:53], 1, v38
	s_andn2_b64 vcc, exec, s[74:75]
	s_cbranch_vccnz .LBB0_729
	ds_read_b128 v[170:173], v244 offset:32
	s_branch .LBB0_730

; #define PG8_LAS __attribute__((address_space(3)))
; __device__ __forceinline__ float dpp_ror1(float v) { return __builtin_bit_cast(float, __builtin_amdgcn_update_dpp(0, __builtin_bit_cast(int, v), 0x121, 0xf, 0xf, false)); }
; __device__ __forceinline__ float dpp_ror15(float v) { return __builtin_bit_cast(float, __builtin_amdgcn_update_dpp(0, __builtin_bit_cast(int, v), 0x12F, 0xf, 0xf, false)); }
;     __device__ __forceinline__ void operator()(const f32x4 (&acc)[2][2][4][2], const Unit& u, int wr, int wc, int fr, int fq) const {
;     ...
;                     for (int bj = 0; bj < 2; ++bj) { const f32x4 cur = acc[ai][bj][m][n];
;                         f32x4 su = cur, sd = cur;
;                         if (m > 0) { if (fr == 15) su = acc[ai][bj][m > 0 ? m - 1 : 0][n]; }
;                         if (m < 3) { if (fr == 0) sd = acc[ai][bj][m < 3 ? m + 1 : 3][n]; }
;                         f32x4 up, dn;
;                         up[0] = dpp_ror1(su[0]); up[1] = dpp_ror1(su[1]); up[2] = dpp_ror1(su[2]); up[3] = dpp_ror1(su[3]);
;                         dn[0] = dpp_ror15(sd[0]); dn[1] = dpp_ror15(sd[1]); dn[2] = dpp_ror15(sd[2]); dn[3] = dpp_ror15(sd[3]);
;                         if (m == 0) { f32x4 halo = zero4; if (blk > 0) halo = *(const PG8_LAS f32x4*)(xb + (((((blk - 1) * 2 + 1) * 4 + wc) * 4 + fq) * 16 + (bj * 2 + n) * 4)); if (fr == 0) up = halo; }
;                         if (m == 3) { f32x4 halo = zero4; if (blk < 3) halo = *(const PG8_LAS f32x4*)(xb + (((((blk + 1) * 2 + 0) * 4 + wc) * 4 + fq) * 16 + (bj * 2 + n) * 4)); if (fr == 15) dn = halo; }
;                         if (edge) { if (!upok) up = zero4; if (!dnok) dn = zero4; }
.LBB0_736:
	s_or_b64 exec, exec, s[0:1]
	v_cndmask_b32_e64 v40, v159, v167, s[4:5]
	v_cndmask_b32_e64 v41, v158, v166, s[4:5]
	v_cndmask_b32_e64 v167, v158, v150, s[6:7]
	v_cndmask_b32_e64 v172, v159, v151, s[6:7]
	v_cndmask_b32_e64 v173, v160, v152, s[6:7]
	v_mov_b32_dpp v166, v167 row_ror:15 row_mask:0xf bank_mask:0xf
	v_add_u32_e32 v178, s48, v231
	v_cndmask_b32_e64 v38, v161, v169, s[4:5]
	v_mov_b32_dpp v167, v172 row_ror:15 row_mask:0xf bank_mask:0xf
	v_cndmask_b32_e64 v39, v160, v168, s[4:5]
	v_cndmask_b32_e64 v174, v161, v153, s[6:7]
	v_mov_b32_dpp v172, v173 row_ror:15 row_mask:0xf bank_mask:0xf
	v_cmp_lt_i32_e64 s[16:17], 0, v178
	v_cmp_le_i32_e64 s[22:23], s49, v178
	v_mov_b32_dpp v168, v41 row_ror:1 row_mask:0xf bank_mask:0xf
	v_mov_b32_dpp v169, v40 row_ror:1 row_mask:0xf bank_mask:0xf
	v_mov_b32_dpp v170, v39 row_ror:1 row_mask:0xf bank_mask:0xf
	v_mov_b32_dpp v171, v38 row_ror:1 row_mask:0xf bank_mask:0xf
	s_and_b64 vcc, exec, s[10:11]
	v_mov_b32_dpp v173, v174 row_ror:15 row_mask:0xf bank_mask:0xf
	s_cbranch_vccnz .LBB0_740
	s_and_saveexec_b64 s[0:1], s[22:23]
	v_mov_b32_e32 v173, 0
	v_mov_b32_e32 v172, 0
	v_mov_b32_e32 v167, 0
	v_mov_b32_e32 v166, 0
	s_or_b64 exec, exec, s[0:1]
	v_cndmask_b32_e64 v171, 0, v171, s[16:17]
	v_cndmask_b32_e64 v170, 0, v170, s[16:17]
	v_cndmask_b32_e64 v169, 0, v169, s[16:17]
	v_cndmask_b32_e64 v168, 0, v168, s[16:17]
.LBB0_740:
	v_cndmask_b32_e64 v177, v154, v146, s[6:7]
	v_cndmask_b32_e64 v39, v156, v164, s[4:5]
	v_cndmask_b32_e64 v164, v155, v147, s[6:7]
	v_mov_b32_dpp v176, v177 row_ror:15 row_mask:0xf bank_mask:0xf
	v_cndmask_b32_e64 v38, v157, v165, s[4:5]
	v_cndmask_b32_e64 v165, v156, v148, s[6:7]
	v_mov_b32_dpp v177, v164 row_ror:15 row_mask:0xf bank_mask:0xf
	v_cndmask_b32_e64 v40, v155, v163, s[4:5]
	v_cndmask_b32_e64 v41, v154, v162, s[4:5]
	v_cndmask_b32_e64 v179, v157, v149, s[6:7]
	v_mov_b32_dpp v164, v165 row_ror:15 row_mask:0xf bank_mask:0xf
	v_mov_b32_dpp v174, v41 row_ror:1 row_mask:0xf bank_mask:0xf
	v_mov_b32_dpp v175, v40 row_ror:1 row_mask:0xf bank_mask:0xf
	v_mov_b32_dpp v162, v39 row_ror:1 row_mask:0xf bank_mask:0xf
	v_mov_b32_dpp v163, v38 row_ror:1 row_mask:0xf bank_mask:0xf
	s_and_b64 vcc, exec, s[10:11]
	v_mov_b32_dpp v165, v179 row_ror:15 row_mask:0xf bank_mask:0xf
	s_cbranch_vccnz .LBB0_744
	s_and_saveexec_b64 s[0:1], s[22:23]
	v_mov_b32_e32 v165, 0
	v_mov_b32_e32 v164, 0
	v_mov_b32_e32 v177, 0
	v_mov_b32_e32 v176, 0
	s_or_b64 exec, exec, s[0:1]
	v_cndmask_b32_e64 v163, 0, v163, s[16:17]
	v_cndmask_b32_e64 v162, 0, v162, s[16:17]
	v_cndmask_b32_e64 v175, 0, v175, s[16:17]
	v_cndmask_b32_e64 v174, 0, v174, s[16:17]

; #define PG8_LAS __attribute__((address_space(3)))
; __device__ __forceinline__ float dpp_ror1(float v) { return __builtin_bit_cast(float, __builtin_amdgcn_update_dpp(0, __builtin_bit_cast(int, v), 0x121, 0xf, 0xf, false)); }
; __device__ __forceinline__ float dpp_ror15(float v) { return __builtin_bit_cast(float, __builtin_amdgcn_update_dpp(0, __builtin_bit_cast(int, v), 0x12F, 0xf, 0xf, false)); }
;     __device__ __forceinline__ void operator()(const f32x4 (&acc)[2][2][4][2], const Unit& u, int wr, int wc, int fr, int fq) const {
;     ...
;                     for (int bj = 0; bj < 2; ++bj) { const f32x4 cur = acc[ai][bj][m][n];
;                         f32x4 su = cur, sd = cur;
;                         if (m > 0) { if (fr == 15) su = acc[ai][bj][m > 0 ? m - 1 : 0][n]; }
;                         if (m < 3) { if (fr == 0) sd = acc[ai][bj][m < 3 ? m + 1 : 3][n]; }
;                         f32x4 up, dn;
;                         up[0] = dpp_ror1(su[0]); up[1] = dpp_ror1(su[1]); up[2] = dpp_ror1(su[2]); up[3] = dpp_ror1(su[3]);
;                         dn[0] = dpp_ror15(sd[0]); dn[1] = dpp_ror15(sd[1]); dn[2] = dpp_ror15(sd[2]); dn[3] = dpp_ror15(sd[3]);
;                         if (m == 0) { f32x4 halo = zero4; if (blk > 0) halo = *(const PG8_LAS f32x4*)(xb + (((((blk - 1) * 2 + 1) * 4 + wc) * 4 + fq) * 16 + (bj * 2 + n) * 4)); if (fr == 0) up = halo; }
;                         if (m == 3) { f32x4 halo = zero4; if (blk < 3) halo = *(const PG8_LAS f32x4*)(xb + (((((blk + 1) * 2 + 0) * 4 + wc) * 4 + fq) * 16 + (bj * 2 + n) * 4)); if (fr == 15) dn = halo; }
;                         if (edge) { if (!upok) up = zero4; if (!dnok) dn = zero4; }
.LBB0_746:
	s_or_b64 exec, exec, s[0:1]
	v_cndmask_b32_e64 v40, v151, v159, s[4:5]
	v_cndmask_b32_e64 v41, v150, v158, s[4:5]
	v_cndmask_b32_e64 v159, v150, v142, s[6:7]
	v_cndmask_b32_e64 v164, v151, v143, s[6:7]
	v_cndmask_b32_e64 v165, v152, v144, s[6:7]
	v_mov_b32_dpp v158, v159 row_ror:15 row_mask:0xf bank_mask:0xf
	v_add_u32_e32 v170, s48, v232
	v_cndmask_b32_e64 v38, v153, v161, s[4:5]
	v_mov_b32_dpp v159, v164 row_ror:15 row_mask:0xf bank_mask:0xf
	v_cndmask_b32_e64 v39, v152, v160, s[4:5]
	v_cndmask_b32_e64 v166, v153, v145, s[6:7]
	v_mov_b32_dpp v164, v165 row_ror:15 row_mask:0xf bank_mask:0xf
	v_cmp_lt_i32_e64 s[18:19], 0, v170
	v_cmp_le_i32_e64 s[26:27], s49, v170
	v_mov_b32_dpp v160, v41 row_ror:1 row_mask:0xf bank_mask:0xf
	v_mov_b32_dpp v161, v40 row_ror:1 row_mask:0xf bank_mask:0xf
	v_mov_b32_dpp v162, v39 row_ror:1 row_mask:0xf bank_mask:0xf
	v_mov_b32_dpp v163, v38 row_ror:1 row_mask:0xf bank_mask:0xf
	s_and_b64 vcc, exec, s[10:11]
	v_mov_b32_dpp v165, v166 row_ror:15 row_mask:0xf bank_mask:0xf
	s_cbranch_vccnz .LBB0_750
	s_and_saveexec_b64 s[0:1], s[26:27]
	v_mov_b32_e32 v165, 0
	v_mov_b32_e32 v164, 0
	v_mov_b32_e32 v159, 0
	v_mov_b32_e32 v158, 0
	s_or_b64 exec, exec, s[0:1]
	v_cndmask_b32_e64 v163, 0, v163, s[18:19]
	v_cndmask_b32_e64 v162, 0, v162, s[18:19]
	v_cndmask_b32_e64 v161, 0, v161, s[18:19]
	v_cndmask_b32_e64 v160, 0, v160, s[18:19]
.LBB0_750:
	v_cndmask_b32_e64 v169, v146, v138, s[6:7]
	v_cndmask_b32_e64 v39, v148, v156, s[4:5]
	v_cndmask_b32_e64 v156, v147, v139, s[6:7]
	v_mov_b32_dpp v168, v169 row_ror:15 row_mask:0xf bank_mask:0xf
	v_cndmask_b32_e64 v38, v149, v157, s[4:5]
	v_cndmask_b32_e64 v157, v148, v140, s[6:7]
	v_mov_b32_dpp v169, v156 row_ror:15 row_mask:0xf bank_mask:0xf
	v_cndmask_b32_e64 v40, v147, v155, s[4:5]
	v_cndmask_b32_e64 v41, v146, v154, s[4:5]
	v_cndmask_b32_e64 v171, v149, v141, s[6:7]
	v_mov_b32_dpp v156, v157 row_ror:15 row_mask:0xf bank_mask:0xf
	v_mov_b32_dpp v166, v41 row_ror:1 row_mask:0xf bank_mask:0xf
	v_mov_b32_dpp v167, v40 row_ror:1 row_mask:0xf bank_mask:0xf
	v_mov_b32_dpp v154, v39 row_ror:1 row_mask:0xf bank_mask:0xf
	v_mov_b32_dpp v155, v38 row_ror:1 row_mask:0xf bank_mask:0xf
	s_and_b64 vcc, exec, s[10:11]
	v_mov_b32_dpp v157, v171 row_ror:15 row_mask:0xf bank_mask:0xf
	s_cbranch_vccnz .LBB0_754
	s_and_saveexec_b64 s[0:1], s[26:27]
	v_mov_b32_e32 v157, 0
	v_mov_b32_e32 v156, 0
	v_mov_b32_e32 v169, 0
	v_mov_b32_e32 v168, 0
	s_or_b64 exec, exec, s[0:1]
	v_cndmask_b32_e64 v155, 0, v155, s[18:19]
	v_cndmask_b32_e64 v154, 0, v154, s[18:19]
	v_cndmask_b32_e64 v167, 0, v167, s[18:19]
	v_cndmask_b32_e64 v166, 0, v166, s[18:19]

; #define PG8_LAS __attribute__((address_space(3)))
; __device__ __forceinline__ float dpp_ror1(float v) { return __builtin_bit_cast(float, __builtin_amdgcn_update_dpp(0, __builtin_bit_cast(int, v), 0x121, 0xf, 0xf, false)); }
; __device__ __forceinline__ float dpp_ror15(float v) { return __builtin_bit_cast(float, __builtin_amdgcn_update_dpp(0, __builtin_bit_cast(int, v), 0x12F, 0xf, 0xf, false)); }
;     __device__ __forceinline__ void operator()(const f32x4 (&acc)[2][2][4][2], const Unit& u, int wr, int wc, int fr, int fq) const {
;     ...
;                     for (int bj = 0; bj < 2; ++bj) { const f32x4 cur = acc[ai][bj][m][n];
;                         f32x4 su = cur, sd = cur;
;                         if (m > 0) { if (fr == 15) su = acc[ai][bj][m > 0 ? m - 1 : 0][n]; }
;                         if (m < 3) { if (fr == 0) sd = acc[ai][bj][m < 3 ? m + 1 : 3][n]; }
;                         f32x4 up, dn;
;                         up[0] = dpp_ror1(su[0]); up[1] = dpp_ror1(su[1]); up[2] = dpp_ror1(su[2]); up[3] = dpp_ror1(su[3]);
;                         dn[0] = dpp_ror15(sd[0]); dn[1] = dpp_ror15(sd[1]); dn[2] = dpp_ror15(sd[2]); dn[3] = dpp_ror15(sd[3]);
;                         if (m == 0) { f32x4 halo = zero4; if (blk > 0) halo = *(const PG8_LAS f32x4*)(xb + (((((blk - 1) * 2 + 1) * 4 + wc) * 4 + fq) * 16 + (bj * 2 + n) * 4)); if (fr == 0) up = halo; }
;                         if (m == 3) { f32x4 halo = zero4; if (blk < 3) halo = *(const PG8_LAS f32x4*)(xb + (((((blk + 1) * 2 + 0) * 4 + wc) * 4 + fq) * 16 + (bj * 2 + n) * 4)); if (fr == 15) dn = halo; }
.LBB0_756:
	s_or_b64 exec, exec, s[0:1]
	v_readlane_b32 s0, v255, 15
	v_cndmask_b32_e64 v38, v145, v153, s[4:5]
	v_readlane_b32 s1, v255, 16
	v_cndmask_b32_e64 v39, v144, v152, s[4:5]
	v_cndmask_b32_e64 v40, v143, v151, s[4:5]
	v_cndmask_b32_e64 v41, v142, v150, s[4:5]
	v_mov_b32_dpp v157, v38 row_ror:1 row_mask:0xf bank_mask:0xf
	v_cndmask_b32_e64 v38, 0, 1, s[0:1]
	v_mov_b32_dpp v154, v41 row_ror:1 row_mask:0xf bank_mask:0xf
	v_mov_b32_dpp v155, v40 row_ror:1 row_mask:0xf bank_mask:0xf
	v_mov_b32_dpp v156, v39 row_ror:1 row_mask:0xf bank_mask:0xf
	v_mov_b32_dpp v158, v142 row_ror:15 row_mask:0xf bank_mask:0xf
	v_mov_b32_dpp v160, v143 row_ror:15 row_mask:0xf bank_mask:0xf
	v_mov_b32_dpp v161, v144 row_ror:15 row_mask:0xf bank_mask:0xf
	v_mov_b32_dpp v159, v145 row_ror:15 row_mask:0xf bank_mask:0xf
	v_mov_b32_e32 v150, 0
	v_cmp_ne_u32_e64 s[38:39], 1, v38
	s_andn2_b64 vcc, exec, s[0:1]
	v_mov_b32_e32 v151, 0
	v_mov_b32_e32 v152, 0
	v_mov_b32_e32 v153, 0
	s_cbranch_vccnz .LBB0_758
	ds_read_b128 v[150:153], v240 offset:2048

; #define PG8_LAS __attribute__((address_space(3)))
; __device__ __forceinline__ float dpp_ror1(float v) { return __builtin_bit_cast(float, __builtin_amdgcn_update_dpp(0, __builtin_bit_cast(int, v), 0x121, 0xf, 0xf, false)); }
; __device__ __forceinline__ float dpp_ror15(float v) { return __builtin_bit_cast(float, __builtin_amdgcn_update_dpp(0, __builtin_bit_cast(int, v), 0x12F, 0xf, 0xf, false)); }
;     __device__ __forceinline__ void operator()(const f32x4 (&acc)[2][2][4][2], const Unit& u, int wr, int wc, int fr, int fq) const {
;     ...
;                     for (int bj = 0; bj < 2; ++bj) { const f32x4 cur = acc[ai][bj][m][n];
;                         f32x4 su = cur, sd = cur;
;                         if (m > 0) { if (fr == 15) su = acc[ai][bj][m > 0 ? m - 1 : 0][n]; }
;                         if (m < 3) { if (fr == 0) sd = acc[ai][bj][m < 3 ? m + 1 : 3][n]; }
;                         f32x4 up, dn;
;                         up[0] = dpp_ror1(su[0]); up[1] = dpp_ror1(su[1]); up[2] = dpp_ror1(su[2]); up[3] = dpp_ror1(su[3]);
;                         dn[0] = dpp_ror15(sd[0]); dn[1] = dpp_ror15(sd[1]); dn[2] = dpp_ror15(sd[2]); dn[3] = dpp_ror15(sd[3]);
;                         if (m == 0) { f32x4 halo = zero4; if (blk > 0) halo = *(const PG8_LAS f32x4*)(xb + (((((blk - 1) * 2 + 1) * 4 + wc) * 4 + fq) * 16 + (bj * 2 + n) * 4)); if (fr == 0) up = halo; }
;                         if (m == 3) { f32x4 halo = zero4; if (blk < 3) halo = *(const PG8_LAS f32x4*)(xb + (((((blk + 1) * 2 + 0) * 4 + wc) * 4 + fq) * 16 + (bj * 2 + n) * 4)); if (fr == 15) dn = halo; }
.LBB0_762:
	v_cndmask_b32_e64 v38, v141, v149, s[4:5]
	v_cndmask_b32_e64 v39, v140, v148, s[4:5]
	v_cndmask_b32_e64 v40, v139, v147, s[4:5]
	v_cndmask_b32_e64 v41, v138, v146, s[4:5]
	s_nop 1
	v_mov_b32_dpp v160, v41 row_ror:1 row_mask:0xf bank_mask:0xf
	v_mov_b32_dpp v161, v40 row_ror:1 row_mask:0xf bank_mask:0xf
	v_mov_b32_dpp v158, v39 row_ror:1 row_mask:0xf bank_mask:0xf
	v_mov_b32_dpp v159, v38 row_ror:1 row_mask:0xf bank_mask:0xf
	v_mov_b32_dpp v162, v138 row_ror:15 row_mask:0xf bank_mask:0xf
	v_mov_b32_dpp v163, v139 row_ror:15 row_mask:0xf bank_mask:0xf
	v_mov_b32_dpp v166, v140 row_ror:15 row_mask:0xf bank_mask:0xf
	v_mov_b32_dpp v165, v141 row_ror:15 row_mask:0xf bank_mask:0xf
	v_mov_b32_e32 v146, 0
	s_and_b64 vcc, exec, s[38:39]
	v_mov_b32_e32 v147, 0
	v_mov_b32_e32 v148, 0
	v_mov_b32_e32 v149, 0
	s_cbranch_vccnz .LBB0_764
	ds_read_b128 v[146:149], v240 offset:2080

; #define PG8_LAS __attribute__((address_space(3)))
; __device__ __forceinline__ float dpp_ror1(float v) { return __builtin_bit_cast(float, __builtin_amdgcn_update_dpp(0, __builtin_bit_cast(int, v), 0x121, 0xf, 0xf, false)); }
; __device__ __forceinline__ float dpp_ror15(float v) { return __builtin_bit_cast(float, __builtin_amdgcn_update_dpp(0, __builtin_bit_cast(int, v), 0x12F, 0xf, 0xf, false)); }
;     __device__ __forceinline__ void operator()(const f32x4 (&acc)[2][2][4][2], const Unit& u, int wr, int wc, int fr, int fq) const {
;     ...
;                     for (int bj = 0; bj < 2; ++bj) { const f32x4 cur = acc[ai][bj][m][n];
;                         f32x4 su = cur, sd = cur;
;                         if (m > 0) { if (fr == 15) su = acc[ai][bj][m > 0 ? m - 1 : 0][n]; }
;                         if (m < 3) { if (fr == 0) sd = acc[ai][bj][m < 3 ? m + 1 : 3][n]; }
;                         f32x4 up, dn;
;                         up[0] = dpp_ror1(su[0]); up[1] = dpp_ror1(su[1]); up[2] = dpp_ror1(su[2]); up[3] = dpp_ror1(su[3]);
;                         dn[0] = dpp_ror15(sd[0]); dn[1] = dpp_ror15(sd[1]); dn[2] = dpp_ror15(sd[2]); dn[3] = dpp_ror15(sd[3]);
;                         if (m == 0) { f32x4 halo = zero4; if (blk > 0) halo = *(const PG8_LAS f32x4*)(xb + (((((blk - 1) * 2 + 1) * 4 + wc) * 4 + fq) * 16 + (bj * 2 + n) * 4)); if (fr == 0) up = halo; }
.LBB0_770:
	s_or_b64 exec, exec, s[0:1]
	v_readlane_b32 s0, v255, 1
	v_cndmask_b32_e64 v38, v105, v97, s[6:7]
	v_readlane_b32 s1, v255, 2
	v_cndmask_b32_e64 v39, v104, v96, s[6:7]
	v_cndmask_b32_e64 v40, v103, v95, s[6:7]
	v_cndmask_b32_e64 v41, v102, v94, s[6:7]
	v_mov_b32_dpp v145, v38 row_ror:15 row_mask:0xf bank_mask:0xf
	v_cndmask_b32_e64 v38, 0, 1, s[0:1]
	v_mov_b32_dpp v148, v102 row_ror:1 row_mask:0xf bank_mask:0xf
	v_mov_b32_dpp v149, v103 row_ror:1 row_mask:0xf bank_mask:0xf
	v_mov_b32_dpp v146, v104 row_ror:1 row_mask:0xf bank_mask:0xf
	v_mov_b32_dpp v147, v105 row_ror:1 row_mask:0xf bank_mask:0xf
	v_mov_b32_dpp v142, v41 row_ror:15 row_mask:0xf bank_mask:0xf
	v_mov_b32_dpp v143, v40 row_ror:15 row_mask:0xf bank_mask:0xf
	v_mov_b32_dpp v144, v39 row_ror:15 row_mask:0xf bank_mask:0xf
	v_mov_b32_e32 v138, 0
	v_cmp_ne_u32_e64 s[44:45], 1, v38
	s_andn2_b64 vcc, exec, s[0:1]
	v_mov_b32_e32 v139, 0
	v_mov_b32_e32 v140, 0
	v_mov_b32_e32 v141, 0
	s_cbranch_vccnz .LBB0_772
	v_readlane_b32 s0, v255, 26
	s_nop 1
	v_add_u32_e32 v38, s0, v230
	ds_read_b128 v[138:141], v38

; #define PG8_LAS __attribute__((address_space(3)))
; __device__ __forceinline__ float dpp_ror1(float v) { return __builtin_bit_cast(float, __builtin_amdgcn_update_dpp(0, __builtin_bit_cast(int, v), 0x121, 0xf, 0xf, false)); }
; __device__ __forceinline__ float dpp_ror15(float v) { return __builtin_bit_cast(float, __builtin_amdgcn_update_dpp(0, __builtin_bit_cast(int, v), 0x12F, 0xf, 0xf, false)); }
;     __device__ __forceinline__ void operator()(const f32x4 (&acc)[2][2][4][2], const Unit& u, int wr, int wc, int fr, int fq) const {
;     ...
;                     for (int bj = 0; bj < 2; ++bj) { const f32x4 cur = acc[ai][bj][m][n];
;                         f32x4 su = cur, sd = cur;
;                         if (m > 0) { if (fr == 15) su = acc[ai][bj][m > 0 ? m - 1 : 0][n]; }
;                         if (m < 3) { if (fr == 0) sd = acc[ai][bj][m < 3 ? m + 1 : 3][n]; }
;                         f32x4 up, dn;
;                         up[0] = dpp_ror1(su[0]); up[1] = dpp_ror1(su[1]); up[2] = dpp_ror1(su[2]); up[3] = dpp_ror1(su[3]);
;                         dn[0] = dpp_ror15(sd[0]); dn[1] = dpp_ror15(sd[1]); dn[2] = dpp_ror15(sd[2]); dn[3] = dpp_ror15(sd[3]);
;                         if (m == 0) { f32x4 halo = zero4; if (blk > 0) halo = *(const PG8_LAS f32x4*)(xb + (((((blk - 1) * 2 + 1) * 4 + wc) * 4 + fq) * 16 + (bj * 2 + n) * 4)); if (fr == 0) up = halo; }
.LBB0_776:
	v_cndmask_b32_e64 v38, v101, v93, s[6:7]
	v_cndmask_b32_e64 v39, v100, v92, s[6:7]
	v_cndmask_b32_e64 v40, v99, v91, s[6:7]
	v_cndmask_b32_e64 v41, v98, v90, s[6:7]
	v_mov_b32_dpp v155, v98 row_ror:1 row_mask:0xf bank_mask:0xf
	v_mov_b32_dpp v156, v99 row_ror:1 row_mask:0xf bank_mask:0xf
	v_mov_b32_dpp v157, v100 row_ror:1 row_mask:0xf bank_mask:0xf
	v_mov_b32_dpp v158, v101 row_ror:1 row_mask:0xf bank_mask:0xf
	v_mov_b32_dpp v152, v41 row_ror:15 row_mask:0xf bank_mask:0xf
	v_mov_b32_dpp v153, v40 row_ror:15 row_mask:0xf bank_mask:0xf
	v_mov_b32_dpp v150, v39 row_ror:15 row_mask:0xf bank_mask:0xf
	v_mov_b32_dpp v151, v38 row_ror:15 row_mask:0xf bank_mask:0xf
	v_mov_b32_e32 v138, 0
	s_and_b64 vcc, exec, s[44:45]
	v_mov_b32_e32 v139, 0
	v_mov_b32_e32 v140, 0
	v_mov_b32_e32 v141, 0
	s_cbranch_vccnz .LBB0_778
	v_readlane_b32 s0, v255, 26
	s_nop 1
	v_add_u32_e32 v38, s0, v230
	ds_read_b128 v[138:141], v38 offset:32

; #define PG8_LAS __attribute__((address_space(3)))
; __device__ __forceinline__ float dpp_ror1(float v) { return __builtin_bit_cast(float, __builtin_amdgcn_update_dpp(0, __builtin_bit_cast(int, v), 0x121, 0xf, 0xf, false)); }
; __device__ __forceinline__ float dpp_ror15(float v) { return __builtin_bit_cast(float, __builtin_amdgcn_update_dpp(0, __builtin_bit_cast(int, v), 0x12F, 0xf, 0xf, false)); }
;     __device__ __forceinline__ void operator()(const f32x4 (&acc)[2][2][4][2], const Unit& u, int wr, int wc, int fr, int fq) const {
;     ...
;                     for (int bj = 0; bj < 2; ++bj) { const f32x4 cur = acc[ai][bj][m][n];
;                         f32x4 su = cur, sd = cur;
;                         if (m > 0) { if (fr == 15) su = acc[ai][bj][m > 0 ? m - 1 : 0][n]; }
;                         if (m < 3) { if (fr == 0) sd = acc[ai][bj][m < 3 ? m + 1 : 3][n]; }
;                         f32x4 up, dn;
;                         up[0] = dpp_ror1(su[0]); up[1] = dpp_ror1(su[1]); up[2] = dpp_ror1(su[2]); up[3] = dpp_ror1(su[3]);
;                         dn[0] = dpp_ror15(sd[0]); dn[1] = dpp_ror15(sd[1]); dn[2] = dpp_ror15(sd[2]); dn[3] = dpp_ror15(sd[3]);
;                         if (m == 0) { f32x4 halo = zero4; if (blk > 0) halo = *(const PG8_LAS f32x4*)(xb + (((((blk - 1) * 2 + 1) * 4 + wc) * 4 + fq) * 16 + (bj * 2 + n) * 4)); if (fr == 0) up = halo; }
;                         if (m == 3) { f32x4 halo = zero4; if (blk < 3) halo = *(const PG8_LAS f32x4*)(xb + (((((blk + 1) * 2 + 0) * 4 + wc) * 4 + fq) * 16 + (bj * 2 + n) * 4)); if (fr == 15) dn = halo; }
;                         if (edge) { if (!upok) up = zero4; if (!dnok) dn = zero4; }
.LBB0_784:
	s_or_b64 exec, exec, s[0:1]
	v_cndmask_b32_e64 v40, v95, v103, s[4:5]
	v_cndmask_b32_e64 v41, v94, v102, s[4:5]
	v_cndmask_b32_e64 v103, v94, v86, s[6:7]
	v_cndmask_b32_e64 v140, v95, v87, s[6:7]
	v_cndmask_b32_e64 v141, v96, v88, s[6:7]
	v_mov_b32_dpp v102, v103 row_ror:15 row_mask:0xf bank_mask:0xf
	v_add_u32_e32 v146, s48, v235
	v_cndmask_b32_e64 v38, v97, v105, s[4:5]
	v_mov_b32_dpp v103, v140 row_ror:15 row_mask:0xf bank_mask:0xf
	v_cndmask_b32_e64 v39, v96, v104, s[4:5]
	v_cndmask_b32_e64 v142, v97, v89, s[6:7]
	v_mov_b32_dpp v140, v141 row_ror:15 row_mask:0xf bank_mask:0xf
	v_cmp_lt_i32_e64 s[30:31], 0, v146
	v_cmp_le_i32_e64 s[42:43], s49, v146
	v_mov_b32_dpp v104, v41 row_ror:1 row_mask:0xf bank_mask:0xf
	v_mov_b32_dpp v105, v40 row_ror:1 row_mask:0xf bank_mask:0xf
	v_mov_b32_dpp v138, v39 row_ror:1 row_mask:0xf bank_mask:0xf
	v_mov_b32_dpp v139, v38 row_ror:1 row_mask:0xf bank_mask:0xf
	s_and_b64 vcc, exec, s[10:11]
	v_mov_b32_dpp v141, v142 row_ror:15 row_mask:0xf bank_mask:0xf
	s_cbranch_vccnz .LBB0_788
	s_and_saveexec_b64 s[0:1], s[42:43]
	v_mov_b32_e32 v141, 0
	v_mov_b32_e32 v140, 0
	v_mov_b32_e32 v103, 0
	v_mov_b32_e32 v102, 0
	s_or_b64 exec, exec, s[0:1]
	v_cndmask_b32_e64 v139, 0, v139, s[30:31]
	v_cndmask_b32_e64 v138, 0, v138, s[30:31]
	v_cndmask_b32_e64 v105, 0, v105, s[30:31]
	v_cndmask_b32_e64 v104, 0, v104, s[30:31]
.LBB0_788:
	v_cndmask_b32_e64 v145, v90, v82, s[6:7]
	v_cndmask_b32_e64 v39, v92, v100, s[4:5]
	v_cndmask_b32_e64 v100, v91, v83, s[6:7]
	v_mov_b32_dpp v144, v145 row_ror:15 row_mask:0xf bank_mask:0xf
	v_cndmask_b32_e64 v38, v93, v101, s[4:5]
	v_cndmask_b32_e64 v101, v92, v84, s[6:7]
	v_mov_b32_dpp v145, v100 row_ror:15 row_mask:0xf bank_mask:0xf
	v_cndmask_b32_e64 v40, v91, v99, s[4:5]
	v_cndmask_b32_e64 v41, v90, v98, s[4:5]
	v_cndmask_b32_e64 v147, v93, v85, s[6:7]
	v_mov_b32_dpp v100, v101 row_ror:15 row_mask:0xf bank_mask:0xf
	v_mov_b32_dpp v142, v41 row_ror:1 row_mask:0xf bank_mask:0xf
	v_mov_b32_dpp v143, v40 row_ror:1 row_mask:0xf bank_mask:0xf
	v_mov_b32_dpp v98, v39 row_ror:1 row_mask:0xf bank_mask:0xf
	v_mov_b32_dpp v99, v38 row_ror:1 row_mask:0xf bank_mask:0xf
	s_and_b64 vcc, exec, s[10:11]
	v_mov_b32_dpp v101, v147 row_ror:15 row_mask:0xf bank_mask:0xf
	s_cbranch_vccnz .LBB0_792
	s_and_saveexec_b64 s[0:1], s[42:43]
	v_mov_b32_e32 v101, 0
	v_mov_b32_e32 v100, 0
	v_mov_b32_e32 v145, 0
	v_mov_b32_e32 v144, 0
	s_or_b64 exec, exec, s[0:1]
	v_cndmask_b32_e64 v99, 0, v99, s[30:31]
	v_cndmask_b32_e64 v98, 0, v98, s[30:31]
	v_cndmask_b32_e64 v143, 0, v143, s[30:31]
	v_cndmask_b32_e64 v142, 0, v142, s[30:31]

; #define PG8_LAS __attribute__((address_space(3)))
; __device__ __forceinline__ float dpp_ror1(float v) { return __builtin_bit_cast(float, __builtin_amdgcn_update_dpp(0, __builtin_bit_cast(int, v), 0x121, 0xf, 0xf, false)); }
; __device__ __forceinline__ float dpp_ror15(float v) { return __builtin_bit_cast(float, __builtin_amdgcn_update_dpp(0, __builtin_bit_cast(int, v), 0x12F, 0xf, 0xf, false)); }
;     __device__ __forceinline__ void operator()(const f32x4 (&acc)[2][2][4][2], const Unit& u, int wr, int wc, int fr, int fq) const {
;     ...
;                     for (int bj = 0; bj < 2; ++bj) { const f32x4 cur = acc[ai][bj][m][n];
;                         f32x4 su = cur, sd = cur;
;                         if (m > 0) { if (fr == 15) su = acc[ai][bj][m > 0 ? m - 1 : 0][n]; }
;                         if (m < 3) { if (fr == 0) sd = acc[ai][bj][m < 3 ? m + 1 : 3][n]; }
;                         f32x4 up, dn;
;                         up[0] = dpp_ror1(su[0]); up[1] = dpp_ror1(su[1]); up[2] = dpp_ror1(su[2]); up[3] = dpp_ror1(su[3]);
;                         dn[0] = dpp_ror15(sd[0]); dn[1] = dpp_ror15(sd[1]); dn[2] = dpp_ror15(sd[2]); dn[3] = dpp_ror15(sd[3]);
;                         if (m == 0) { f32x4 halo = zero4; if (blk > 0) halo = *(const PG8_LAS f32x4*)(xb + (((((blk - 1) * 2 + 1) * 4 + wc) * 4 + fq) * 16 + (bj * 2 + n) * 4)); if (fr == 0) up = halo; }
;                         if (m == 3) { f32x4 halo = zero4; if (blk < 3) halo = *(const PG8_LAS f32x4*)(xb + (((((blk + 1) * 2 + 0) * 4 + wc) * 4 + fq) * 16 + (bj * 2 + n) * 4)); if (fr == 15) dn = halo; }
;                         if (edge) { if (!upok) up = zero4; if (!dnok) dn = zero4; }
.LBB0_794:
	s_or_b64 exec, exec, s[0:1]
	v_cndmask_b32_e64 v40, v87, v95, s[4:5]
	v_cndmask_b32_e64 v41, v86, v94, s[4:5]
	v_cndmask_b32_e64 v95, v86, v78, s[6:7]
	v_cndmask_b32_e64 v100, v87, v79, s[6:7]
	v_cndmask_b32_e64 v101, v88, v80, s[6:7]
	v_mov_b32_dpp v94, v95 row_ror:15 row_mask:0xf bank_mask:0xf
	v_add_u32_e32 v138, s48, v236
	v_cndmask_b32_e64 v38, v89, v97, s[4:5]
	v_mov_b32_dpp v95, v100 row_ror:15 row_mask:0xf bank_mask:0xf
	v_cndmask_b32_e64 v39, v88, v96, s[4:5]
	v_cndmask_b32_e64 v102, v89, v81, s[6:7]
	v_mov_b32_dpp v100, v101 row_ror:15 row_mask:0xf bank_mask:0xf
	v_cmp_lt_i32_e64 s[36:37], 0, v138
	v_cmp_le_i32_e64 s[46:47], s49, v138
	v_mov_b32_dpp v96, v41 row_ror:1 row_mask:0xf bank_mask:0xf
	v_mov_b32_dpp v97, v40 row_ror:1 row_mask:0xf bank_mask:0xf
	v_mov_b32_dpp v98, v39 row_ror:1 row_mask:0xf bank_mask:0xf
	v_mov_b32_dpp v99, v38 row_ror:1 row_mask:0xf bank_mask:0xf
	s_and_b64 vcc, exec, s[10:11]
	v_mov_b32_dpp v101, v102 row_ror:15 row_mask:0xf bank_mask:0xf
	s_cbranch_vccnz .LBB0_798
	s_and_saveexec_b64 s[0:1], s[46:47]
	v_mov_b32_e32 v101, 0
	v_mov_b32_e32 v100, 0
	v_mov_b32_e32 v95, 0
	v_mov_b32_e32 v94, 0
	s_or_b64 exec, exec, s[0:1]
	v_cndmask_b32_e64 v99, 0, v99, s[36:37]
	v_cndmask_b32_e64 v98, 0, v98, s[36:37]
	v_cndmask_b32_e64 v97, 0, v97, s[36:37]
	v_cndmask_b32_e64 v96, 0, v96, s[36:37]
.LBB0_798:
	v_cndmask_b32_e64 v105, v82, v74, s[6:7]
	v_cndmask_b32_e64 v39, v84, v92, s[4:5]
	v_cndmask_b32_e64 v92, v83, v75, s[6:7]
	v_mov_b32_dpp v104, v105 row_ror:15 row_mask:0xf bank_mask:0xf
	v_cndmask_b32_e64 v38, v85, v93, s[4:5]
	v_cndmask_b32_e64 v93, v84, v76, s[6:7]
	v_mov_b32_dpp v105, v92 row_ror:15 row_mask:0xf bank_mask:0xf
	v_cndmask_b32_e64 v40, v83, v91, s[4:5]
	v_cndmask_b32_e64 v41, v82, v90, s[4:5]
	v_cndmask_b32_e64 v139, v85, v77, s[6:7]
	v_mov_b32_dpp v92, v93 row_ror:15 row_mask:0xf bank_mask:0xf
	v_mov_b32_dpp v102, v41 row_ror:1 row_mask:0xf bank_mask:0xf
	v_mov_b32_dpp v103, v40 row_ror:1 row_mask:0xf bank_mask:0xf
	v_mov_b32_dpp v90, v39 row_ror:1 row_mask:0xf bank_mask:0xf
	v_mov_b32_dpp v91, v38 row_ror:1 row_mask:0xf bank_mask:0xf
	s_and_b64 vcc, exec, s[10:11]
	v_mov_b32_dpp v93, v139 row_ror:15 row_mask:0xf bank_mask:0xf
	s_cbranch_vccnz .LBB0_802
	s_and_saveexec_b64 s[0:1], s[46:47]
	v_mov_b32_e32 v93, 0
	v_mov_b32_e32 v92, 0
	v_mov_b32_e32 v105, 0
	v_mov_b32_e32 v104, 0
	s_or_b64 exec, exec, s[0:1]
	v_cndmask_b32_e64 v91, 0, v91, s[36:37]
	v_cndmask_b32_e64 v90, 0, v90, s[36:37]
	v_cndmask_b32_e64 v103, 0, v103, s[36:37]
	v_cndmask_b32_e64 v102, 0, v102, s[36:37]

; #define PG8_LAS __attribute__((address_space(3)))
; __device__ __forceinline__ float dpp_ror1(float v) { return __builtin_bit_cast(float, __builtin_amdgcn_update_dpp(0, __builtin_bit_cast(int, v), 0x121, 0xf, 0xf, false)); }
; __device__ __forceinline__ float dpp_ror15(float v) { return __builtin_bit_cast(float, __builtin_amdgcn_update_dpp(0, __builtin_bit_cast(int, v), 0x12F, 0xf, 0xf, false)); }
;     __device__ __forceinline__ void operator()(const f32x4 (&acc)[2][2][4][2], const Unit& u, int wr, int wc, int fr, int fq) const {
;     ...
;                     for (int bj = 0; bj < 2; ++bj) { const f32x4 cur = acc[ai][bj][m][n];
;                         f32x4 su = cur, sd = cur;
;                         if (m > 0) { if (fr == 15) su = acc[ai][bj][m > 0 ? m - 1 : 0][n]; }
;                         if (m < 3) { if (fr == 0) sd = acc[ai][bj][m < 3 ? m + 1 : 3][n]; }
;                         f32x4 up, dn;
;                         up[0] = dpp_ror1(su[0]); up[1] = dpp_ror1(su[1]); up[2] = dpp_ror1(su[2]); up[3] = dpp_ror1(su[3]);
;                         dn[0] = dpp_ror15(sd[0]); dn[1] = dpp_ror15(sd[1]); dn[2] = dpp_ror15(sd[2]); dn[3] = dpp_ror15(sd[3]);
;                         if (m == 0) { f32x4 halo = zero4; if (blk > 0) halo = *(const PG8_LAS f32x4*)(xb + (((((blk - 1) * 2 + 1) * 4 + wc) * 4 + fq) * 16 + (bj * 2 + n) * 4)); if (fr == 0) up = halo; }
;                         if (m == 3) { f32x4 halo = zero4; if (blk < 3) halo = *(const PG8_LAS f32x4*)(xb + (((((blk + 1) * 2 + 0) * 4 + wc) * 4 + fq) * 16 + (bj * 2 + n) * 4)); if (fr == 15) dn = halo; }
.LBB0_804:
	s_or_b64 exec, exec, s[0:1]
	v_readlane_b32 s0, v255, 17
	v_cndmask_b32_e64 v38, v81, v89, s[4:5]
	v_readlane_b32 s1, v255, 18
	v_cndmask_b32_e64 v39, v80, v88, s[4:5]
	v_cndmask_b32_e64 v40, v79, v87, s[4:5]
	v_cndmask_b32_e64 v41, v78, v86, s[4:5]
	v_mov_b32_dpp v93, v38 row_ror:1 row_mask:0xf bank_mask:0xf
	v_cndmask_b32_e64 v38, 0, 1, s[0:1]
	v_mov_b32_dpp v90, v41 row_ror:1 row_mask:0xf bank_mask:0xf
	v_mov_b32_dpp v91, v40 row_ror:1 row_mask:0xf bank_mask:0xf
	v_mov_b32_dpp v92, v39 row_ror:1 row_mask:0xf bank_mask:0xf
	v_mov_b32_dpp v94, v78 row_ror:15 row_mask:0xf bank_mask:0xf
	v_mov_b32_dpp v96, v79 row_ror:15 row_mask:0xf bank_mask:0xf
	v_mov_b32_dpp v97, v80 row_ror:15 row_mask:0xf bank_mask:0xf
	v_mov_b32_dpp v95, v81 row_ror:15 row_mask:0xf bank_mask:0xf
	v_mov_b32_e32 v86, 0
	v_cmp_ne_u32_e64 s[50:51], 1, v38
	s_andn2_b64 vcc, exec, s[0:1]
	v_mov_b32_e32 v87, 0
	v_mov_b32_e32 v88, 0
	v_mov_b32_e32 v89, 0
	s_cbranch_vccnz .LBB0_806
	ds_read_b128 v[86:89], v241 offset:2048

; #define PG8_LAS __attribute__((address_space(3)))
; __device__ __forceinline__ float dpp_ror1(float v) { return __builtin_bit_cast(float, __builtin_amdgcn_update_dpp(0, __builtin_bit_cast(int, v), 0x121, 0xf, 0xf, false)); }
; __device__ __forceinline__ float dpp_ror15(float v) { return __builtin_bit_cast(float, __builtin_amdgcn_update_dpp(0, __builtin_bit_cast(int, v), 0x12F, 0xf, 0xf, false)); }
;     __device__ __forceinline__ void operator()(const f32x4 (&acc)[2][2][4][2], const Unit& u, int wr, int wc, int fr, int fq) const {
;     ...
;                     for (int bj = 0; bj < 2; ++bj) { const f32x4 cur = acc[ai][bj][m][n];
;                         f32x4 su = cur, sd = cur;
;                         if (m > 0) { if (fr == 15) su = acc[ai][bj][m > 0 ? m - 1 : 0][n]; }
;                         if (m < 3) { if (fr == 0) sd = acc[ai][bj][m < 3 ? m + 1 : 3][n]; }
;                         f32x4 up, dn;
;                         up[0] = dpp_ror1(su[0]); up[1] = dpp_ror1(su[1]); up[2] = dpp_ror1(su[2]); up[3] = dpp_ror1(su[3]);
;                         dn[0] = dpp_ror15(sd[0]); dn[1] = dpp_ror15(sd[1]); dn[2] = dpp_ror15(sd[2]); dn[3] = dpp_ror15(sd[3]);
;                         if (m == 0) { f32x4 halo = zero4; if (blk > 0) halo = *(const PG8_LAS f32x4*)(xb + (((((blk - 1) * 2 + 1) * 4 + wc) * 4 + fq) * 16 + (bj * 2 + n) * 4)); if (fr == 0) up = halo; }
;                         if (m == 3) { f32x4 halo = zero4; if (blk < 3) halo = *(const PG8_LAS f32x4*)(xb + (((((blk + 1) * 2 + 0) * 4 + wc) * 4 + fq) * 16 + (bj * 2 + n) * 4)); if (fr == 15) dn = halo; }
.LBB0_810:
	v_cndmask_b32_e64 v38, v77, v85, s[4:5]
	v_cndmask_b32_e64 v39, v76, v84, s[4:5]
	v_cndmask_b32_e64 v40, v75, v83, s[4:5]
	v_cndmask_b32_e64 v41, v74, v82, s[4:5]
	s_nop 1
	v_mov_b32_dpp v96, v41 row_ror:1 row_mask:0xf bank_mask:0xf
	v_mov_b32_dpp v97, v40 row_ror:1 row_mask:0xf bank_mask:0xf
	v_mov_b32_dpp v94, v39 row_ror:1 row_mask:0xf bank_mask:0xf
	v_mov_b32_dpp v95, v38 row_ror:1 row_mask:0xf bank_mask:0xf
	v_mov_b32_dpp v98, v74 row_ror:15 row_mask:0xf bank_mask:0xf
	v_mov_b32_dpp v99, v75 row_ror:15 row_mask:0xf bank_mask:0xf
	v_mov_b32_dpp v101, v76 row_ror:15 row_mask:0xf bank_mask:0xf
	v_mov_b32_dpp v100, v77 row_ror:15 row_mask:0xf bank_mask:0xf
	v_mov_b32_e32 v82, 0
	s_and_b64 vcc, exec, s[50:51]
	v_mov_b32_e32 v83, 0
	v_mov_b32_e32 v84, 0
	v_mov_b32_e32 v85, 0
	s_cbranch_vccnz .LBB0_812
	ds_read_b128 v[82:85], v241 offset:2080

; #define PG8_LAS __attribute__((address_space(3)))
; __device__ __forceinline__ float dpp_ror1(float v) { return __builtin_bit_cast(float, __builtin_amdgcn_update_dpp(0, __builtin_bit_cast(int, v), 0x121, 0xf, 0xf, false)); }
; __device__ __forceinline__ float dpp_ror15(float v) { return __builtin_bit_cast(float, __builtin_amdgcn_update_dpp(0, __builtin_bit_cast(int, v), 0x12F, 0xf, 0xf, false)); }
;     __device__ __forceinline__ void operator()(const f32x4 (&acc)[2][2][4][2], const Unit& u, int wr, int wc, int fr, int fq) const {
;     ...
;             if (n == 1) {
; #pragma unroll
;                 for (int bj = 0; bj < 2; ++bj) { const int col = bj * 2816 + ch0 + 4;
;                     w0[bj] = *(const f32x4*)(cw + col); w1[bj] = *(const f32x4*)(cw + 5632 + col); w2[bj] = *(const f32x4*)(cw + 11264 + col); bb[bj] = *(const f32x4*)(cb + col); } }
; #pragma unroll
;             for (int ai = 0; ai < 2; ++ai) { const int blk = ai * 2 + wr;
; #pragma unroll
;                 for (int m = 0; m < 4; ++m) { const int r = 128 * ai + 64 * wr + 16 * m + fr, t = tstart + r;
;                     const bool upok = t >= 1, dnok = (t + 1) < T, store_ok = (r >= vlo) && (r < vhi) && (t < T);
;                     f32x4 res[2];
; #pragma unroll
;                     for (int bj = 0; bj < 2; ++bj) { const f32x4 cur = acc[ai][bj][m][n];
;                         f32x4 su = cur, sd = cur;
;                         if (m > 0) { if (fr == 15) su = acc[ai][bj][m > 0 ? m - 1 : 0][n]; }
;                         if (m < 3) { if (fr == 0) sd = acc[ai][bj][m < 3 ? m + 1 : 3][n]; }
;                         f32x4 up, dn;
;                         up[0] = dpp_ror1(su[0]); up[1] = dpp_ror1(su[1]); up[2] = dpp_ror1(su[2]); up[3] = dpp_ror1(su[3]);
;                         dn[0] = dpp_ror15(sd[0]); dn[1] = dpp_ror15(sd[1]); dn[2] = dpp_ror15(sd[2]); dn[3] = dpp_ror15(sd[3]);
;                         if (m == 0) { f32x4 halo = zero4; if (blk > 0) halo = *(const PG8_LAS f32x4*)(xb + (((((blk - 1) * 2 + 1) * 4 + wc) * 4 + fq) * 16 + (bj * 2 + n) * 4)); if (fr == 0) up = halo; }
.LBB0_818:
	s_or_b64 exec, exec, s[54:55]
	v_or_b32_e32 v38, 4, v194
	v_ashrrev_i32_e32 v39, 31, v38
	v_lshlrev_b64 v[38:39], 2, v[38:39]
	v_lshl_add_u64 v[40:41], s[66:67], 0, v[38:39]
	v_lshl_add_u64 v[38:39], s[68:69], 0, v[38:39]
	global_load_dwordx4 v[98:101], v[196:197], off offset:16
	global_load_dwordx4 v[94:97], v[40:41], off
	global_load_dwordx4 v[74:77], v[38:39], off
	global_load_dwordx4 v[102:105], v[198:199], off offset:16
	v_add_u32_e32 v38, 0xb04, v194
	v_ashrrev_i32_e32 v39, 31, v38
	v_lshlrev_b64 v[38:39], 2, v[38:39]
	v_lshl_add_u64 v[40:41], s[62:63], 0, v[38:39]
	v_lshl_add_u64 v[78:79], s[66:67], 0, v[38:39]
	global_load_dwordx4 v[82:85], v[40:41], off
	global_load_dwordx4 v[86:89], v[78:79], off
	v_lshl_add_u64 v[40:41], s[68:69], 0, v[38:39]
	v_lshl_add_u64 v[38:39], s[64:65], 0, v[38:39]
	global_load_dwordx4 v[78:81], v[40:41], off
	global_load_dwordx4 v[90:93], v[38:39], off
	v_cndmask_b32_e64 v38, v73, v65, s[6:7]
	v_cndmask_b32_e64 v39, v72, v64, s[6:7]
	v_cndmask_b32_e64 v40, v71, v63, s[6:7]
	v_cndmask_b32_e64 v41, v70, v62, s[6:7]
	s_waitcnt vmcnt(0)
	v_mov_b32_dpp v116, v70 row_ror:1 row_mask:0xf bank_mask:0xf
	v_mov_b32_dpp v117, v71 row_ror:1 row_mask:0xf bank_mask:0xf
	v_mov_b32_dpp v114, v72 row_ror:1 row_mask:0xf bank_mask:0xf
	v_mov_b32_dpp v115, v73 row_ror:1 row_mask:0xf bank_mask:0xf
	v_mov_b32_dpp v110, v41 row_ror:15 row_mask:0xf bank_mask:0xf
	v_mov_b32_dpp v111, v40 row_ror:15 row_mask:0xf bank_mask:0xf
	v_mov_b32_dpp v112, v39 row_ror:15 row_mask:0xf bank_mask:0xf
	s_and_b64 vcc, exec, s[52:53]
	v_mov_b32_dpp v113, v38 row_ror:15 row_mask:0xf bank_mask:0xf
	s_cbranch_vccnz .LBB0_820
	v_add_u32_e32 v38, 0xfffffc10, v240
	ds_read_b128 v[106:109], v38
	s_branch .LBB0_821

; #define PG8_LAS __attribute__((address_space(3)))
; __device__ __forceinline__ float dpp_ror1(float v) { return __builtin_bit_cast(float, __builtin_amdgcn_update_dpp(0, __builtin_bit_cast(int, v), 0x121, 0xf, 0xf, false)); }
; __device__ __forceinline__ float dpp_ror15(float v) { return __builtin_bit_cast(float, __builtin_amdgcn_update_dpp(0, __builtin_bit_cast(int, v), 0x12F, 0xf, 0xf, false)); }
;     __device__ __forceinline__ void operator()(const f32x4 (&acc)[2][2][4][2], const Unit& u, int wr, int wc, int fr, int fq) const {
;     ...
;                     for (int bj = 0; bj < 2; ++bj) { const f32x4 cur = acc[ai][bj][m][n];
;                         f32x4 su = cur, sd = cur;
;                         if (m > 0) { if (fr == 15) su = acc[ai][bj][m > 0 ? m - 1 : 0][n]; }
;                         if (m < 3) { if (fr == 0) sd = acc[ai][bj][m < 3 ? m + 1 : 3][n]; }
;                         f32x4 up, dn;
;                         up[0] = dpp_ror1(su[0]); up[1] = dpp_ror1(su[1]); up[2] = dpp_ror1(su[2]); up[3] = dpp_ror1(su[3]);
;                         dn[0] = dpp_ror15(sd[0]); dn[1] = dpp_ror15(sd[1]); dn[2] = dpp_ror15(sd[2]); dn[3] = dpp_ror15(sd[3]);
;                         if (m == 0) { f32x4 halo = zero4; if (blk > 0) halo = *(const PG8_LAS f32x4*)(xb + (((((blk - 1) * 2 + 1) * 4 + wc) * 4 + fq) * 16 + (bj * 2 + n) * 4)); if (fr == 0) up = halo; }
.LBB0_825:
	v_cndmask_b32_e64 v38, v69, v61, s[6:7]
	v_cndmask_b32_e64 v39, v68, v60, s[6:7]
	v_cndmask_b32_e64 v40, v67, v59, s[6:7]
	v_cndmask_b32_e64 v41, v66, v58, s[6:7]
	v_mov_b32_dpp v122, v66 row_ror:1 row_mask:0xf bank_mask:0xf
	v_mov_b32_dpp v123, v67 row_ror:1 row_mask:0xf bank_mask:0xf
	v_mov_b32_dpp v124, v68 row_ror:1 row_mask:0xf bank_mask:0xf
	v_mov_b32_dpp v125, v69 row_ror:1 row_mask:0xf bank_mask:0xf
	v_mov_b32_dpp v120, v41 row_ror:15 row_mask:0xf bank_mask:0xf
	v_mov_b32_dpp v121, v40 row_ror:15 row_mask:0xf bank_mask:0xf
	v_mov_b32_dpp v118, v39 row_ror:15 row_mask:0xf bank_mask:0xf
	s_and_b64 vcc, exec, s[52:53]
	v_mov_b32_dpp v119, v38 row_ror:15 row_mask:0xf bank_mask:0xf
	s_cbranch_vccnz .LBB0_827
	v_add_u32_e32 v38, 0xfffffc30, v240
	ds_read_b128 v[106:109], v38
	s_branch .LBB0_828

; #define PG8_LAS __attribute__((address_space(3)))
; __device__ __forceinline__ float dpp_ror1(float v) { return __builtin_bit_cast(float, __builtin_amdgcn_update_dpp(0, __builtin_bit_cast(int, v), 0x121, 0xf, 0xf, false)); }
; __device__ __forceinline__ float dpp_ror15(float v) { return __builtin_bit_cast(float, __builtin_amdgcn_update_dpp(0, __builtin_bit_cast(int, v), 0x12F, 0xf, 0xf, false)); }
;     __device__ __forceinline__ void operator()(const f32x4 (&acc)[2][2][4][2], const Unit& u, int wr, int wc, int fr, int fq) const {
;     ...
;                     for (int bj = 0; bj < 2; ++bj) { const f32x4 cur = acc[ai][bj][m][n];
;                         f32x4 su = cur, sd = cur;
;                         if (m > 0) { if (fr == 15) su = acc[ai][bj][m > 0 ? m - 1 : 0][n]; }
;                         if (m < 3) { if (fr == 0) sd = acc[ai][bj][m < 3 ? m + 1 : 3][n]; }
;                         f32x4 up, dn;
;                         up[0] = dpp_ror1(su[0]); up[1] = dpp_ror1(su[1]); up[2] = dpp_ror1(su[2]); up[3] = dpp_ror1(su[3]);
;                         dn[0] = dpp_ror15(sd[0]); dn[1] = dpp_ror15(sd[1]); dn[2] = dpp_ror15(sd[2]); dn[3] = dpp_ror15(sd[3]);
;                         if (m == 0) { f32x4 halo = zero4; if (blk > 0) halo = *(const PG8_LAS f32x4*)(xb + (((((blk - 1) * 2 + 1) * 4 + wc) * 4 + fq) * 16 + (bj * 2 + n) * 4)); if (fr == 0) up = halo; }
;                         if (m == 3) { f32x4 halo = zero4; if (blk < 3) halo = *(const PG8_LAS f32x4*)(xb + (((((blk + 1) * 2 + 0) * 4 + wc) * 4 + fq) * 16 + (bj * 2 + n) * 4)); if (fr == 15) dn = halo; }
;                         if (edge) { if (!upok) up = zero4; if (!dnok) dn = zero4; }
.LBB0_834:
	s_or_b64 exec, exec, s[12:13]
	v_cndmask_b32_e64 v40, v63, v71, s[4:5]
	v_cndmask_b32_e64 v41, v62, v70, s[4:5]
	v_cndmask_b32_e64 v71, v62, v54, s[6:7]
	v_cndmask_b32_e64 v108, v63, v55, s[6:7]
	v_cndmask_b32_e64 v109, v64, v56, s[6:7]
	v_mov_b32_dpp v70, v71 row_ror:15 row_mask:0xf bank_mask:0xf
	v_cndmask_b32_e64 v38, v65, v73, s[4:5]
	v_cndmask_b32_e64 v39, v64, v72, s[4:5]
	v_mov_b32_dpp v71, v108 row_ror:15 row_mask:0xf bank_mask:0xf
	v_cndmask_b32_e64 v110, v65, v57, s[6:7]
	v_mov_b32_dpp v108, v109 row_ror:15 row_mask:0xf bank_mask:0xf
	v_mov_b32_dpp v72, v41 row_ror:1 row_mask:0xf bank_mask:0xf
	v_mov_b32_dpp v73, v40 row_ror:1 row_mask:0xf bank_mask:0xf
	v_mov_b32_dpp v106, v39 row_ror:1 row_mask:0xf bank_mask:0xf
	v_mov_b32_dpp v107, v38 row_ror:1 row_mask:0xf bank_mask:0xf
	s_and_b64 vcc, exec, s[10:11]
	v_mov_b32_dpp v109, v110 row_ror:15 row_mask:0xf bank_mask:0xf
	s_cbranch_vccnz .LBB0_838
	s_and_saveexec_b64 s[2:3], s[22:23]
	v_mov_b32_e32 v109, 0
	v_mov_b32_e32 v108, 0
	v_mov_b32_e32 v71, 0
	v_mov_b32_e32 v70, 0
	s_or_b64 exec, exec, s[2:3]
	v_cndmask_b32_e64 v107, 0, v107, s[16:17]
	v_cndmask_b32_e64 v106, 0, v106, s[16:17]
	v_cndmask_b32_e64 v73, 0, v73, s[16:17]
	v_cndmask_b32_e64 v72, 0, v72, s[16:17]
.LBB0_838:
	v_cndmask_b32_e64 v113, v58, v50, s[6:7]
	v_cndmask_b32_e64 v39, v60, v68, s[4:5]
	v_cndmask_b32_e64 v68, v59, v51, s[6:7]
	v_mov_b32_dpp v112, v113 row_ror:15 row_mask:0xf bank_mask:0xf
	v_cndmask_b32_e64 v38, v61, v69, s[4:5]
	v_cndmask_b32_e64 v69, v60, v52, s[6:7]
	v_mov_b32_dpp v113, v68 row_ror:15 row_mask:0xf bank_mask:0xf
	v_cndmask_b32_e64 v40, v59, v67, s[4:5]
	v_cndmask_b32_e64 v41, v58, v66, s[4:5]
	v_cndmask_b32_e64 v114, v61, v53, s[6:7]
	v_mov_b32_dpp v68, v69 row_ror:15 row_mask:0xf bank_mask:0xf
	v_mov_b32_dpp v110, v41 row_ror:1 row_mask:0xf bank_mask:0xf
	v_mov_b32_dpp v111, v40 row_ror:1 row_mask:0xf bank_mask:0xf
	v_mov_b32_dpp v66, v39 row_ror:1 row_mask:0xf bank_mask:0xf
	v_mov_b32_dpp v67, v38 row_ror:1 row_mask:0xf bank_mask:0xf
	s_and_b64 vcc, exec, s[10:11]
	v_mov_b32_dpp v69, v114 row_ror:15 row_mask:0xf bank_mask:0xf
	s_cbranch_vccnz .LBB0_842
	s_and_saveexec_b64 s[2:3], s[22:23]
	v_mov_b32_e32 v69, 0
	v_mov_b32_e32 v68, 0
	v_mov_b32_e32 v113, 0
	v_mov_b32_e32 v112, 0
	s_or_b64 exec, exec, s[2:3]
	v_cndmask_b32_e64 v67, 0, v67, s[16:17]
	v_cndmask_b32_e64 v66, 0, v66, s[16:17]
	v_cndmask_b32_e64 v111, 0, v111, s[16:17]
	v_cndmask_b32_e64 v110, 0, v110, s[16:17]

; #define PG8_LAS __attribute__((address_space(3)))
; __device__ __forceinline__ float dpp_ror1(float v) { return __builtin_bit_cast(float, __builtin_amdgcn_update_dpp(0, __builtin_bit_cast(int, v), 0x121, 0xf, 0xf, false)); }
; __device__ __forceinline__ float dpp_ror15(float v) { return __builtin_bit_cast(float, __builtin_amdgcn_update_dpp(0, __builtin_bit_cast(int, v), 0x12F, 0xf, 0xf, false)); }
;     __device__ __forceinline__ void operator()(const f32x4 (&acc)[2][2][4][2], const Unit& u, int wr, int wc, int fr, int fq) const {
;     ...
;                     for (int bj = 0; bj < 2; ++bj) { const f32x4 cur = acc[ai][bj][m][n];
;                         f32x4 su = cur, sd = cur;
;                         if (m > 0) { if (fr == 15) su = acc[ai][bj][m > 0 ? m - 1 : 0][n]; }
;                         if (m < 3) { if (fr == 0) sd = acc[ai][bj][m < 3 ? m + 1 : 3][n]; }
;                         f32x4 up, dn;
;                         up[0] = dpp_ror1(su[0]); up[1] = dpp_ror1(su[1]); up[2] = dpp_ror1(su[2]); up[3] = dpp_ror1(su[3]);
;                         dn[0] = dpp_ror15(sd[0]); dn[1] = dpp_ror15(sd[1]); dn[2] = dpp_ror15(sd[2]); dn[3] = dpp_ror15(sd[3]);
;                         if (m == 0) { f32x4 halo = zero4; if (blk > 0) halo = *(const PG8_LAS f32x4*)(xb + (((((blk - 1) * 2 + 1) * 4 + wc) * 4 + fq) * 16 + (bj * 2 + n) * 4)); if (fr == 0) up = halo; }
;                         if (m == 3) { f32x4 halo = zero4; if (blk < 3) halo = *(const PG8_LAS f32x4*)(xb + (((((blk + 1) * 2 + 0) * 4 + wc) * 4 + fq) * 16 + (bj * 2 + n) * 4)); if (fr == 15) dn = halo; }
;                         if (edge) { if (!upok) up = zero4; if (!dnok) dn = zero4; }
.LBB0_844:
	s_or_b64 exec, exec, s[2:3]
	v_cndmask_b32_e64 v40, v55, v63, s[4:5]
	v_cndmask_b32_e64 v41, v54, v62, s[4:5]
	v_cndmask_b32_e64 v63, v54, v46, s[6:7]
	v_cndmask_b32_e64 v68, v55, v47, s[6:7]
	v_cndmask_b32_e64 v69, v56, v48, s[6:7]
	v_mov_b32_dpp v62, v63 row_ror:15 row_mask:0xf bank_mask:0xf
	v_cndmask_b32_e64 v38, v57, v65, s[4:5]
	v_cndmask_b32_e64 v39, v56, v64, s[4:5]
	v_mov_b32_dpp v63, v68 row_ror:15 row_mask:0xf bank_mask:0xf
	v_cndmask_b32_e64 v70, v57, v49, s[6:7]
	v_mov_b32_dpp v68, v69 row_ror:15 row_mask:0xf bank_mask:0xf
	v_mov_b32_dpp v64, v41 row_ror:1 row_mask:0xf bank_mask:0xf
	v_mov_b32_dpp v65, v40 row_ror:1 row_mask:0xf bank_mask:0xf
	v_mov_b32_dpp v66, v39 row_ror:1 row_mask:0xf bank_mask:0xf
	v_mov_b32_dpp v67, v38 row_ror:1 row_mask:0xf bank_mask:0xf
	s_and_b64 vcc, exec, s[10:11]
	v_mov_b32_dpp v69, v70 row_ror:15 row_mask:0xf bank_mask:0xf
	s_cbranch_vccnz .LBB0_848
	s_and_saveexec_b64 s[2:3], s[26:27]
	v_mov_b32_e32 v69, 0
	v_mov_b32_e32 v68, 0
	v_mov_b32_e32 v63, 0
	v_mov_b32_e32 v62, 0
	s_or_b64 exec, exec, s[2:3]
	v_cndmask_b32_e64 v67, 0, v67, s[18:19]
	v_cndmask_b32_e64 v66, 0, v66, s[18:19]
	v_cndmask_b32_e64 v65, 0, v65, s[18:19]
	v_cndmask_b32_e64 v64, 0, v64, s[18:19]
.LBB0_848:
	v_cndmask_b32_e64 v73, v50, v42, s[6:7]
	v_cndmask_b32_e64 v39, v52, v60, s[4:5]
	v_cndmask_b32_e64 v60, v51, v43, s[6:7]
	v_mov_b32_dpp v72, v73 row_ror:15 row_mask:0xf bank_mask:0xf
	v_cndmask_b32_e64 v38, v53, v61, s[4:5]
	v_cndmask_b32_e64 v61, v52, v44, s[6:7]
	v_mov_b32_dpp v73, v60 row_ror:15 row_mask:0xf bank_mask:0xf
	v_cndmask_b32_e64 v40, v51, v59, s[4:5]
	v_cndmask_b32_e64 v41, v50, v58, s[4:5]
	v_cndmask_b32_e64 v106, v53, v45, s[6:7]
	v_mov_b32_dpp v60, v61 row_ror:15 row_mask:0xf bank_mask:0xf
	v_mov_b32_dpp v70, v41 row_ror:1 row_mask:0xf bank_mask:0xf
	v_mov_b32_dpp v71, v40 row_ror:1 row_mask:0xf bank_mask:0xf
	v_mov_b32_dpp v58, v39 row_ror:1 row_mask:0xf bank_mask:0xf
	v_mov_b32_dpp v59, v38 row_ror:1 row_mask:0xf bank_mask:0xf
	s_and_b64 vcc, exec, s[10:11]
	v_mov_b32_dpp v61, v106 row_ror:15 row_mask:0xf bank_mask:0xf
	s_cbranch_vccnz .LBB0_852
	s_and_saveexec_b64 s[2:3], s[26:27]
	v_mov_b32_e32 v61, 0
	v_mov_b32_e32 v60, 0
	v_mov_b32_e32 v73, 0
	v_mov_b32_e32 v72, 0
	s_or_b64 exec, exec, s[2:3]
	v_cndmask_b32_e64 v59, 0, v59, s[18:19]
	v_cndmask_b32_e64 v58, 0, v58, s[18:19]
	v_cndmask_b32_e64 v71, 0, v71, s[18:19]
	v_cndmask_b32_e64 v70, 0, v70, s[18:19]

; #define PG8_LAS __attribute__((address_space(3)))
; __device__ __forceinline__ float dpp_ror1(float v) { return __builtin_bit_cast(float, __builtin_amdgcn_update_dpp(0, __builtin_bit_cast(int, v), 0x121, 0xf, 0xf, false)); }
; __device__ __forceinline__ float dpp_ror15(float v) { return __builtin_bit_cast(float, __builtin_amdgcn_update_dpp(0, __builtin_bit_cast(int, v), 0x12F, 0xf, 0xf, false)); }
;     __device__ __forceinline__ void operator()(const f32x4 (&acc)[2][2][4][2], const Unit& u, int wr, int wc, int fr, int fq) const {
;     ...
;                     for (int bj = 0; bj < 2; ++bj) { const f32x4 cur = acc[ai][bj][m][n];
;                         f32x4 su = cur, sd = cur;
;                         if (m > 0) { if (fr == 15) su = acc[ai][bj][m > 0 ? m - 1 : 0][n]; }
;                         if (m < 3) { if (fr == 0) sd = acc[ai][bj][m < 3 ? m + 1 : 3][n]; }
;                         f32x4 up, dn;
;                         up[0] = dpp_ror1(su[0]); up[1] = dpp_ror1(su[1]); up[2] = dpp_ror1(su[2]); up[3] = dpp_ror1(su[3]);
;                         dn[0] = dpp_ror15(sd[0]); dn[1] = dpp_ror15(sd[1]); dn[2] = dpp_ror15(sd[2]); dn[3] = dpp_ror15(sd[3]);
;                         if (m == 0) { f32x4 halo = zero4; if (blk > 0) halo = *(const PG8_LAS f32x4*)(xb + (((((blk - 1) * 2 + 1) * 4 + wc) * 4 + fq) * 16 + (bj * 2 + n) * 4)); if (fr == 0) up = halo; }
;                         if (m == 3) { f32x4 halo = zero4; if (blk < 3) halo = *(const PG8_LAS f32x4*)(xb + (((((blk + 1) * 2 + 0) * 4 + wc) * 4 + fq) * 16 + (bj * 2 + n) * 4)); if (fr == 15) dn = halo; }
.LBB0_854:
	s_or_b64 exec, exec, s[2:3]
	v_cndmask_b32_e64 v38, v49, v57, s[4:5]
	v_cndmask_b32_e64 v39, v48, v56, s[4:5]
	v_cndmask_b32_e64 v40, v47, v55, s[4:5]
	v_cndmask_b32_e64 v41, v46, v54, s[4:5]
	s_nop 1
	v_mov_b32_dpp v58, v41 row_ror:1 row_mask:0xf bank_mask:0xf
	v_mov_b32_dpp v59, v40 row_ror:1 row_mask:0xf bank_mask:0xf
	v_mov_b32_dpp v60, v39 row_ror:1 row_mask:0xf bank_mask:0xf
	v_mov_b32_dpp v61, v38 row_ror:1 row_mask:0xf bank_mask:0xf
	v_mov_b32_dpp v62, v46 row_ror:15 row_mask:0xf bank_mask:0xf
	v_mov_b32_dpp v64, v47 row_ror:15 row_mask:0xf bank_mask:0xf
	v_mov_b32_dpp v65, v48 row_ror:15 row_mask:0xf bank_mask:0xf
	v_mov_b32_dpp v63, v49 row_ror:15 row_mask:0xf bank_mask:0xf
	v_mov_b32_e32 v54, 0
	s_and_b64 vcc, exec, s[38:39]
	v_mov_b32_e32 v55, 0
	v_mov_b32_e32 v56, 0
	v_mov_b32_e32 v57, 0
	s_cbranch_vccnz .LBB0_856
	ds_read_b128 v[54:57], v240 offset:2064

; #define PG8_LAS __attribute__((address_space(3)))
; __device__ __forceinline__ float dpp_ror1(float v) { return __builtin_bit_cast(float, __builtin_amdgcn_update_dpp(0, __builtin_bit_cast(int, v), 0x121, 0xf, 0xf, false)); }
; __device__ __forceinline__ float dpp_ror15(float v) { return __builtin_bit_cast(float, __builtin_amdgcn_update_dpp(0, __builtin_bit_cast(int, v), 0x12F, 0xf, 0xf, false)); }
;     __device__ __forceinline__ void operator()(const f32x4 (&acc)[2][2][4][2], const Unit& u, int wr, int wc, int fr, int fq) const {
;     ...
;                     for (int bj = 0; bj < 2; ++bj) { const f32x4 cur = acc[ai][bj][m][n];
;                         f32x4 su = cur, sd = cur;
;                         if (m > 0) { if (fr == 15) su = acc[ai][bj][m > 0 ? m - 1 : 0][n]; }
;                         if (m < 3) { if (fr == 0) sd = acc[ai][bj][m < 3 ? m + 1 : 3][n]; }
;                         f32x4 up, dn;
;                         up[0] = dpp_ror1(su[0]); up[1] = dpp_ror1(su[1]); up[2] = dpp_ror1(su[2]); up[3] = dpp_ror1(su[3]);
;                         dn[0] = dpp_ror15(sd[0]); dn[1] = dpp_ror15(sd[1]); dn[2] = dpp_ror15(sd[2]); dn[3] = dpp_ror15(sd[3]);
;                         if (m == 0) { f32x4 halo = zero4; if (blk > 0) halo = *(const PG8_LAS f32x4*)(xb + (((((blk - 1) * 2 + 1) * 4 + wc) * 4 + fq) * 16 + (bj * 2 + n) * 4)); if (fr == 0) up = halo; }
;                         if (m == 3) { f32x4 halo = zero4; if (blk < 3) halo = *(const PG8_LAS f32x4*)(xb + (((((blk + 1) * 2 + 0) * 4 + wc) * 4 + fq) * 16 + (bj * 2 + n) * 4)); if (fr == 15) dn = halo; }
.LBB0_860:
	v_cndmask_b32_e64 v38, v45, v53, s[4:5]
	v_cndmask_b32_e64 v39, v44, v52, s[4:5]
	v_cndmask_b32_e64 v40, v43, v51, s[4:5]
	v_cndmask_b32_e64 v41, v42, v50, s[4:5]
	s_nop 1
	v_mov_b32_dpp v64, v41 row_ror:1 row_mask:0xf bank_mask:0xf
	v_mov_b32_dpp v65, v40 row_ror:1 row_mask:0xf bank_mask:0xf
	v_mov_b32_dpp v62, v39 row_ror:1 row_mask:0xf bank_mask:0xf
	v_mov_b32_dpp v63, v38 row_ror:1 row_mask:0xf bank_mask:0xf
	v_mov_b32_dpp v66, v42 row_ror:15 row_mask:0xf bank_mask:0xf
	v_mov_b32_dpp v67, v43 row_ror:15 row_mask:0xf bank_mask:0xf
	v_mov_b32_dpp v69, v44 row_ror:15 row_mask:0xf bank_mask:0xf
	v_mov_b32_dpp v68, v45 row_ror:15 row_mask:0xf bank_mask:0xf
	v_mov_b32_e32 v50, 0
	s_and_b64 vcc, exec, s[38:39]
	v_mov_b32_e32 v51, 0
	v_mov_b32_e32 v52, 0
	v_mov_b32_e32 v53, 0
	s_cbranch_vccnz .LBB0_862
	ds_read_b128 v[50:53], v240 offset:2096

; #define PG8_LAS __attribute__((address_space(3)))
; __device__ __forceinline__ float dpp_ror1(float v) { return __builtin_bit_cast(float, __builtin_amdgcn_update_dpp(0, __builtin_bit_cast(int, v), 0x121, 0xf, 0xf, false)); }
; __device__ __forceinline__ float dpp_ror15(float v) { return __builtin_bit_cast(float, __builtin_amdgcn_update_dpp(0, __builtin_bit_cast(int, v), 0x12F, 0xf, 0xf, false)); }
;     __device__ __forceinline__ void operator()(const f32x4 (&acc)[2][2][4][2], const Unit& u, int wr, int wc, int fr, int fq) const {
;     ...
;                     for (int bj = 0; bj < 2; ++bj) { const f32x4 cur = acc[ai][bj][m][n];
;                         f32x4 su = cur, sd = cur;
;                         if (m > 0) { if (fr == 15) su = acc[ai][bj][m > 0 ? m - 1 : 0][n]; }
;                         if (m < 3) { if (fr == 0) sd = acc[ai][bj][m < 3 ? m + 1 : 3][n]; }
;                         f32x4 up, dn;
;                         up[0] = dpp_ror1(su[0]); up[1] = dpp_ror1(su[1]); up[2] = dpp_ror1(su[2]); up[3] = dpp_ror1(su[3]);
;                         dn[0] = dpp_ror15(sd[0]); dn[1] = dpp_ror15(sd[1]); dn[2] = dpp_ror15(sd[2]); dn[3] = dpp_ror15(sd[3]);
;                         if (m == 0) { f32x4 halo = zero4; if (blk > 0) halo = *(const PG8_LAS f32x4*)(xb + (((((blk - 1) * 2 + 1) * 4 + wc) * 4 + fq) * 16 + (bj * 2 + n) * 4)); if (fr == 0) up = halo; }
.LBB0_868:
	s_or_b64 exec, exec, s[2:3]
	v_cndmask_b32_e64 v38, v33, v25, s[6:7]
	v_cndmask_b32_e64 v39, v32, v24, s[6:7]
	v_cndmask_b32_e64 v40, v31, v23, s[6:7]
	v_cndmask_b32_e64 v41, v30, v22, s[6:7]
	v_mov_b32_dpp v52, v30 row_ror:1 row_mask:0xf bank_mask:0xf
	v_mov_b32_dpp v53, v31 row_ror:1 row_mask:0xf bank_mask:0xf
	v_mov_b32_dpp v50, v32 row_ror:1 row_mask:0xf bank_mask:0xf
	v_mov_b32_dpp v51, v33 row_ror:1 row_mask:0xf bank_mask:0xf
	v_mov_b32_dpp v46, v41 row_ror:15 row_mask:0xf bank_mask:0xf
	v_mov_b32_dpp v47, v40 row_ror:15 row_mask:0xf bank_mask:0xf
	v_mov_b32_dpp v48, v39 row_ror:15 row_mask:0xf bank_mask:0xf
	v_mov_b32_dpp v49, v38 row_ror:15 row_mask:0xf bank_mask:0xf
	v_mov_b32_e32 v42, 0
	s_and_b64 vcc, exec, s[44:45]
	v_mov_b32_e32 v43, 0
	v_mov_b32_e32 v44, 0
	v_mov_b32_e32 v45, 0
	v_readlane_b32 s86, v254, 45
	s_movk_i32 s87, 0x3000
	s_cbranch_vccnz .LBB0_870
	v_add_u32_e32 v38, 0xfffffc10, v241
	ds_read_b128 v[42:45], v38

; #define PG8_LAS __attribute__((address_space(3)))
; __device__ __forceinline__ float dpp_ror1(float v) { return __builtin_bit_cast(float, __builtin_amdgcn_update_dpp(0, __builtin_bit_cast(int, v), 0x121, 0xf, 0xf, false)); }
; __device__ __forceinline__ float dpp_ror15(float v) { return __builtin_bit_cast(float, __builtin_amdgcn_update_dpp(0, __builtin_bit_cast(int, v), 0x12F, 0xf, 0xf, false)); }
;     __device__ __forceinline__ void operator()(const f32x4 (&acc)[2][2][4][2], const Unit& u, int wr, int wc, int fr, int fq) const {
;     ...
;                     for (int bj = 0; bj < 2; ++bj) { const f32x4 cur = acc[ai][bj][m][n];
;                         f32x4 su = cur, sd = cur;
;                         if (m > 0) { if (fr == 15) su = acc[ai][bj][m > 0 ? m - 1 : 0][n]; }
;                         if (m < 3) { if (fr == 0) sd = acc[ai][bj][m < 3 ? m + 1 : 3][n]; }
;                         f32x4 up, dn;
;                         up[0] = dpp_ror1(su[0]); up[1] = dpp_ror1(su[1]); up[2] = dpp_ror1(su[2]); up[3] = dpp_ror1(su[3]);
;                         dn[0] = dpp_ror15(sd[0]); dn[1] = dpp_ror15(sd[1]); dn[2] = dpp_ror15(sd[2]); dn[3] = dpp_ror15(sd[3]);
;                         if (m == 0) { f32x4 halo = zero4; if (blk > 0) halo = *(const PG8_LAS f32x4*)(xb + (((((blk - 1) * 2 + 1) * 4 + wc) * 4 + fq) * 16 + (bj * 2 + n) * 4)); if (fr == 0) up = halo; }
.LBB0_874:
	v_cndmask_b32_e64 v38, v29, v21, s[6:7]
	v_cndmask_b32_e64 v39, v28, v20, s[6:7]
	v_cndmask_b32_e64 v40, v27, v19, s[6:7]
	v_cndmask_b32_e64 v41, v26, v18, s[6:7]
	v_mov_b32_dpp v58, v26 row_ror:1 row_mask:0xf bank_mask:0xf
	v_mov_b32_dpp v59, v27 row_ror:1 row_mask:0xf bank_mask:0xf
	v_mov_b32_dpp v60, v28 row_ror:1 row_mask:0xf bank_mask:0xf
	v_mov_b32_dpp v61, v29 row_ror:1 row_mask:0xf bank_mask:0xf
	v_mov_b32_dpp v56, v41 row_ror:15 row_mask:0xf bank_mask:0xf
	v_mov_b32_dpp v57, v40 row_ror:15 row_mask:0xf bank_mask:0xf
	v_mov_b32_dpp v54, v39 row_ror:15 row_mask:0xf bank_mask:0xf
	v_mov_b32_dpp v55, v38 row_ror:15 row_mask:0xf bank_mask:0xf
	v_mov_b32_e32 v42, 0
	s_and_b64 vcc, exec, s[44:45]
	v_mov_b32_e32 v43, 0
	v_mov_b32_e32 v44, 0
	v_mov_b32_e32 v45, 0
	s_cbranch_vccnz .LBB0_876
	v_add_u32_e32 v38, 0xfffffc30, v241
	ds_read_b128 v[42:45], v38

; #define PG8_LAS __attribute__((address_space(3)))
; __device__ __forceinline__ float dpp_ror1(float v) { return __builtin_bit_cast(float, __builtin_amdgcn_update_dpp(0, __builtin_bit_cast(int, v), 0x121, 0xf, 0xf, false)); }
; __device__ __forceinline__ float dpp_ror15(float v) { return __builtin_bit_cast(float, __builtin_amdgcn_update_dpp(0, __builtin_bit_cast(int, v), 0x12F, 0xf, 0xf, false)); }
;     __device__ __forceinline__ void operator()(const f32x4 (&acc)[2][2][4][2], const Unit& u, int wr, int wc, int fr, int fq) const {
;     ...
;                     for (int bj = 0; bj < 2; ++bj) { const f32x4 cur = acc[ai][bj][m][n];
;                         f32x4 su = cur, sd = cur;
;                         if (m > 0) { if (fr == 15) su = acc[ai][bj][m > 0 ? m - 1 : 0][n]; }
;                         if (m < 3) { if (fr == 0) sd = acc[ai][bj][m < 3 ? m + 1 : 3][n]; }
;                         f32x4 up, dn;
;                         up[0] = dpp_ror1(su[0]); up[1] = dpp_ror1(su[1]); up[2] = dpp_ror1(su[2]); up[3] = dpp_ror1(su[3]);
;                         dn[0] = dpp_ror15(sd[0]); dn[1] = dpp_ror15(sd[1]); dn[2] = dpp_ror15(sd[2]); dn[3] = dpp_ror15(sd[3]);
;                         if (m == 0) { f32x4 halo = zero4; if (blk > 0) halo = *(const PG8_LAS f32x4*)(xb + (((((blk - 1) * 2 + 1) * 4 + wc) * 4 + fq) * 16 + (bj * 2 + n) * 4)); if (fr == 0) up = halo; }
;                         if (m == 3) { f32x4 halo = zero4; if (blk < 3) halo = *(const PG8_LAS f32x4*)(xb + (((((blk + 1) * 2 + 0) * 4 + wc) * 4 + fq) * 16 + (bj * 2 + n) * 4)); if (fr == 15) dn = halo; }
;                         if (edge) { if (!upok) up = zero4; if (!dnok) dn = zero4; }
.LBB0_882:
	s_or_b64 exec, exec, s[2:3]
	v_cndmask_b32_e64 v38, v25, v33, s[4:5]
	v_cndmask_b32_e64 v39, v24, v32, s[4:5]
	v_cndmask_b32_e64 v31, v23, v31, s[4:5]
	v_cndmask_b32_e64 v30, v22, v30, s[4:5]
	v_cndmask_b32_e64 v44, v23, v15, s[6:7]
	v_cndmask_b32_e64 v45, v22, v14, s[6:7]
	v_mov_b32_dpp v32, v30 row_ror:1 row_mask:0xf bank_mask:0xf
	v_mov_b32_dpp v33, v31 row_ror:1 row_mask:0xf bank_mask:0xf
	v_cndmask_b32_e64 v40, v25, v17, s[6:7]
	v_cndmask_b32_e64 v41, v24, v16, s[6:7]
	v_mov_b32_dpp v30, v45 row_ror:15 row_mask:0xf bank_mask:0xf
	v_mov_b32_dpp v31, v44 row_ror:15 row_mask:0xf bank_mask:0xf
	v_mov_b32_dpp v42, v39 row_ror:1 row_mask:0xf bank_mask:0xf
	v_mov_b32_dpp v43, v38 row_ror:1 row_mask:0xf bank_mask:0xf
	v_mov_b32_dpp v44, v41 row_ror:15 row_mask:0xf bank_mask:0xf
	s_and_b64 vcc, exec, s[10:11]
	v_mov_b32_dpp v45, v40 row_ror:15 row_mask:0xf bank_mask:0xf
	v_readlane_b32 s89, v254, 46
	s_mov_b32 s88, 0xf800000
	s_cbranch_vccnz .LBB0_886
	s_and_saveexec_b64 s[2:3], s[42:43]
	v_mov_b32_e32 v45, 0
	v_mov_b32_e32 v44, 0
	v_mov_b32_e32 v31, 0
	v_mov_b32_e32 v30, 0
	s_or_b64 exec, exec, s[2:3]
	v_cndmask_b32_e64 v43, 0, v43, s[30:31]
	v_cndmask_b32_e64 v42, 0, v42, s[30:31]
	v_cndmask_b32_e64 v33, 0, v33, s[30:31]
	v_cndmask_b32_e64 v32, 0, v32, s[30:31]
.LBB0_886:
	v_cndmask_b32_e64 v27, v19, v27, s[4:5]
	v_cndmask_b32_e64 v26, v18, v26, s[4:5]
	v_cndmask_b32_e64 v29, v21, v29, s[4:5]
	v_cndmask_b32_e64 v28, v20, v28, s[4:5]
	v_mov_b32_dpp v46, v26 row_ror:1 row_mask:0xf bank_mask:0xf
	v_mov_b32_dpp v47, v27 row_ror:1 row_mask:0xf bank_mask:0xf
	v_cndmask_b32_e64 v38, v21, v13, s[6:7]
	v_cndmask_b32_e64 v39, v20, v12, s[6:7]
	v_cndmask_b32_e64 v40, v19, v11, s[6:7]
	v_cndmask_b32_e64 v41, v18, v10, s[6:7]
	v_mov_b32_dpp v26, v28 row_ror:1 row_mask:0xf bank_mask:0xf
	v_mov_b32_dpp v27, v29 row_ror:1 row_mask:0xf bank_mask:0xf
	v_mov_b32_dpp v48, v41 row_ror:15 row_mask:0xf bank_mask:0xf
	v_mov_b32_dpp v49, v40 row_ror:15 row_mask:0xf bank_mask:0xf
	v_mov_b32_dpp v28, v39 row_ror:15 row_mask:0xf bank_mask:0xf
	s_and_b64 vcc, exec, s[10:11]
	v_mov_b32_dpp v29, v38 row_ror:15 row_mask:0xf bank_mask:0xf
	s_cbranch_vccnz .LBB0_890
	s_and_saveexec_b64 s[2:3], s[42:43]
	v_mov_b32_e32 v29, 0
	v_mov_b32_e32 v28, 0
	v_mov_b32_e32 v49, 0
	v_mov_b32_e32 v48, 0
	s_or_b64 exec, exec, s[2:3]
	v_cndmask_b32_e64 v27, 0, v27, s[30:31]
	v_cndmask_b32_e64 v26, 0, v26, s[30:31]
	v_cndmask_b32_e64 v47, 0, v47, s[30:31]
	v_cndmask_b32_e64 v46, 0, v46, s[30:31]

; #define PG8_LAS __attribute__((address_space(3)))
; __device__ __forceinline__ float dpp_ror1(float v) { return __builtin_bit_cast(float, __builtin_amdgcn_update_dpp(0, __builtin_bit_cast(int, v), 0x121, 0xf, 0xf, false)); }
; __device__ __forceinline__ float dpp_ror15(float v) { return __builtin_bit_cast(float, __builtin_amdgcn_update_dpp(0, __builtin_bit_cast(int, v), 0x12F, 0xf, 0xf, false)); }
;     __device__ __forceinline__ void operator()(const f32x4 (&acc)[2][2][4][2], const Unit& u, int wr, int wc, int fr, int fq) const {
;     ...
;                     for (int bj = 0; bj < 2; ++bj) { const f32x4 cur = acc[ai][bj][m][n];
;                         f32x4 su = cur, sd = cur;
;                         if (m > 0) { if (fr == 15) su = acc[ai][bj][m > 0 ? m - 1 : 0][n]; }
;                         if (m < 3) { if (fr == 0) sd = acc[ai][bj][m < 3 ? m + 1 : 3][n]; }
;                         f32x4 up, dn;
;                         up[0] = dpp_ror1(su[0]); up[1] = dpp_ror1(su[1]); up[2] = dpp_ror1(su[2]); up[3] = dpp_ror1(su[3]);
;                         dn[0] = dpp_ror15(sd[0]); dn[1] = dpp_ror15(sd[1]); dn[2] = dpp_ror15(sd[2]); dn[3] = dpp_ror15(sd[3]);
;                         if (m == 0) { f32x4 halo = zero4; if (blk > 0) halo = *(const PG8_LAS f32x4*)(xb + (((((blk - 1) * 2 + 1) * 4 + wc) * 4 + fq) * 16 + (bj * 2 + n) * 4)); if (fr == 0) up = halo; }
;                         if (m == 3) { f32x4 halo = zero4; if (blk < 3) halo = *(const PG8_LAS f32x4*)(xb + (((((blk + 1) * 2 + 0) * 4 + wc) * 4 + fq) * 16 + (bj * 2 + n) * 4)); if (fr == 15) dn = halo; }
;                         if (edge) { if (!upok) up = zero4; if (!dnok) dn = zero4; }
.LBB0_892:
	s_or_b64 exec, exec, s[2:3]
	v_cndmask_b32_e64 v27, v16, v24, s[4:5]
	v_cndmask_b32_e64 v28, v17, v25, s[4:5]
	v_cndmask_b32_e64 v23, v15, v23, s[4:5]
	v_mov_b32_dpp v26, v27 row_ror:1 row_mask:0xf bank_mask:0xf
	v_cndmask_b32_e64 v22, v14, v22, s[4:5]
	v_cndmask_b32_e64 v29, v16, v8, s[6:7]
	v_mov_b32_dpp v27, v28 row_ror:1 row_mask:0xf bank_mask:0xf
	v_cndmask_b32_e64 v30, v17, v9, s[6:7]
	v_cndmask_b32_e64 v31, v15, v7, s[6:7]
	v_cndmask_b32_e64 v32, v14, v6, s[6:7]
	v_mov_b32_dpp v24, v22 row_ror:1 row_mask:0xf bank_mask:0xf
	v_mov_b32_dpp v25, v23 row_ror:1 row_mask:0xf bank_mask:0xf
	v_mov_b32_dpp v28, v29 row_ror:15 row_mask:0xf bank_mask:0xf
	v_mov_b32_dpp v22, v32 row_ror:15 row_mask:0xf bank_mask:0xf
	v_mov_b32_dpp v23, v31 row_ror:15 row_mask:0xf bank_mask:0xf
	s_and_b64 vcc, exec, s[10:11]
	v_mov_b32_dpp v29, v30 row_ror:15 row_mask:0xf bank_mask:0xf
	v_readlane_b32 s84, v254, 32
	s_cbranch_vccnz .LBB0_896
	s_and_saveexec_b64 s[2:3], s[46:47]
	v_mov_b32_e32 v29, 0
	v_mov_b32_e32 v28, 0
	v_mov_b32_e32 v23, 0
	v_mov_b32_e32 v22, 0
	s_or_b64 exec, exec, s[2:3]
	v_cndmask_b32_e64 v27, 0, v27, s[36:37]
	v_cndmask_b32_e64 v26, 0, v26, s[36:37]
	v_cndmask_b32_e64 v25, 0, v25, s[36:37]
	v_cndmask_b32_e64 v24, 0, v24, s[36:37]
.LBB0_896:
	v_cndmask_b32_e64 v19, v11, v19, s[4:5]
	v_cndmask_b32_e64 v18, v10, v18, s[4:5]
	v_cndmask_b32_e64 v21, v13, v21, s[4:5]
	v_cndmask_b32_e64 v20, v12, v20, s[4:5]
	v_cndmask_b32_e64 v33, v10, v2, s[6:7]
	v_mov_b32_dpp v30, v18 row_ror:1 row_mask:0xf bank_mask:0xf
	v_mov_b32_dpp v31, v19 row_ror:1 row_mask:0xf bank_mask:0xf
	v_cndmask_b32_e64 v38, v13, v5, s[6:7]
	v_cndmask_b32_e64 v39, v12, v4, s[6:7]
	v_cndmask_b32_e64 v40, v11, v3, s[6:7]
	v_mov_b32_dpp v18, v20 row_ror:1 row_mask:0xf bank_mask:0xf
	v_mov_b32_dpp v19, v21 row_ror:1 row_mask:0xf bank_mask:0xf
	v_mov_b32_dpp v32, v33 row_ror:15 row_mask:0xf bank_mask:0xf
	v_mov_b32_dpp v33, v40 row_ror:15 row_mask:0xf bank_mask:0xf
	v_mov_b32_dpp v20, v39 row_ror:15 row_mask:0xf bank_mask:0xf
	s_and_b64 vcc, exec, s[10:11]
	v_mov_b32_dpp v21, v38 row_ror:15 row_mask:0xf bank_mask:0xf
	s_cbranch_vccnz .LBB0_900
	s_and_saveexec_b64 s[2:3], s[46:47]
	v_mov_b32_e32 v21, 0
	v_mov_b32_e32 v20, 0
	v_mov_b32_e32 v33, 0
	v_mov_b32_e32 v32, 0
	s_or_b64 exec, exec, s[2:3]
	v_cndmask_b32_e64 v19, 0, v19, s[36:37]
	v_cndmask_b32_e64 v18, 0, v18, s[36:37]
	v_cndmask_b32_e64 v31, 0, v31, s[36:37]
	v_cndmask_b32_e64 v30, 0, v30, s[36:37]

; #define PG8_LAS __attribute__((address_space(3)))
; __device__ __forceinline__ float dpp_ror1(float v) { return __builtin_bit_cast(float, __builtin_amdgcn_update_dpp(0, __builtin_bit_cast(int, v), 0x121, 0xf, 0xf, false)); }
; __device__ __forceinline__ float dpp_ror15(float v) { return __builtin_bit_cast(float, __builtin_amdgcn_update_dpp(0, __builtin_bit_cast(int, v), 0x12F, 0xf, 0xf, false)); }
;     __device__ __forceinline__ void operator()(const f32x4 (&acc)[2][2][4][2], const Unit& u, int wr, int wc, int fr, int fq) const {
;     ...
;                     for (int bj = 0; bj < 2; ++bj) { const f32x4 cur = acc[ai][bj][m][n];
;                         f32x4 su = cur, sd = cur;
;                         if (m > 0) { if (fr == 15) su = acc[ai][bj][m > 0 ? m - 1 : 0][n]; }
;                         if (m < 3) { if (fr == 0) sd = acc[ai][bj][m < 3 ? m + 1 : 3][n]; }
;                         f32x4 up, dn;
;                         up[0] = dpp_ror1(su[0]); up[1] = dpp_ror1(su[1]); up[2] = dpp_ror1(su[2]); up[3] = dpp_ror1(su[3]);
;                         dn[0] = dpp_ror15(sd[0]); dn[1] = dpp_ror15(sd[1]); dn[2] = dpp_ror15(sd[2]); dn[3] = dpp_ror15(sd[3]);
;                         if (m == 0) { f32x4 halo = zero4; if (blk > 0) halo = *(const PG8_LAS f32x4*)(xb + (((((blk - 1) * 2 + 1) * 4 + wc) * 4 + fq) * 16 + (bj * 2 + n) * 4)); if (fr == 0) up = halo; }
;                         if (m == 3) { f32x4 halo = zero4; if (blk < 3) halo = *(const PG8_LAS f32x4*)(xb + (((((blk + 1) * 2 + 0) * 4 + wc) * 4 + fq) * 16 + (bj * 2 + n) * 4)); if (fr == 15) dn = halo; }
.LBB0_902:
	s_or_b64 exec, exec, s[2:3]
	v_cndmask_b32_e64 v17, v9, v17, s[4:5]
	v_cndmask_b32_e64 v16, v8, v16, s[4:5]
	v_cndmask_b32_e64 v15, v7, v15, s[4:5]
	v_cndmask_b32_e64 v14, v6, v14, s[4:5]
	s_nop 1
	v_mov_b32_dpp v18, v14 row_ror:1 row_mask:0xf bank_mask:0xf
	v_mov_b32_dpp v19, v15 row_ror:1 row_mask:0xf bank_mask:0xf
	v_mov_b32_dpp v20, v16 row_ror:1 row_mask:0xf bank_mask:0xf
	v_mov_b32_dpp v21, v17 row_ror:1 row_mask:0xf bank_mask:0xf
	v_mov_b32_dpp v22, v6 row_ror:15 row_mask:0xf bank_mask:0xf
	v_mov_b32_dpp v24, v7 row_ror:15 row_mask:0xf bank_mask:0xf
	v_mov_b32_dpp v25, v8 row_ror:15 row_mask:0xf bank_mask:0xf
	v_mov_b32_dpp v23, v9 row_ror:15 row_mask:0xf bank_mask:0xf
	v_mov_b32_e32 v14, 0
	s_and_b64 vcc, exec, s[50:51]
	v_mov_b32_e32 v15, 0
	v_mov_b32_e32 v16, 0
	v_mov_b32_e32 v17, 0
	s_cbranch_vccnz .LBB0_904
	ds_read_b128 v[14:17], v241 offset:2064

; #define PG8_LAS __attribute__((address_space(3)))
; __device__ __forceinline__ float dpp_ror1(float v) { return __builtin_bit_cast(float, __builtin_amdgcn_update_dpp(0, __builtin_bit_cast(int, v), 0x121, 0xf, 0xf, false)); }
; __device__ __forceinline__ float dpp_ror15(float v) { return __builtin_bit_cast(float, __builtin_amdgcn_update_dpp(0, __builtin_bit_cast(int, v), 0x12F, 0xf, 0xf, false)); }
;     __device__ __forceinline__ void operator()(const f32x4 (&acc)[2][2][4][2], const Unit& u, int wr, int wc, int fr, int fq) const {
;     ...
;                     for (int bj = 0; bj < 2; ++bj) { const f32x4 cur = acc[ai][bj][m][n];
;                         f32x4 su = cur, sd = cur;
;                         if (m > 0) { if (fr == 15) su = acc[ai][bj][m > 0 ? m - 1 : 0][n]; }
;                         if (m < 3) { if (fr == 0) sd = acc[ai][bj][m < 3 ? m + 1 : 3][n]; }
;                         f32x4 up, dn;
;                         up[0] = dpp_ror1(su[0]); up[1] = dpp_ror1(su[1]); up[2] = dpp_ror1(su[2]); up[3] = dpp_ror1(su[3]);
;                         dn[0] = dpp_ror15(sd[0]); dn[1] = dpp_ror15(sd[1]); dn[2] = dpp_ror15(sd[2]); dn[3] = dpp_ror15(sd[3]);
;                         if (m == 0) { f32x4 halo = zero4; if (blk > 0) halo = *(const PG8_LAS f32x4*)(xb + (((((blk - 1) * 2 + 1) * 4 + wc) * 4 + fq) * 16 + (bj * 2 + n) * 4)); if (fr == 0) up = halo; }
;                         if (m == 3) { f32x4 halo = zero4; if (blk < 3) halo = *(const PG8_LAS f32x4*)(xb + (((((blk + 1) * 2 + 0) * 4 + wc) * 4 + fq) * 16 + (bj * 2 + n) * 4)); if (fr == 15) dn = halo; }
.LBB0_908:
	v_cndmask_b32_e64 v13, v5, v13, s[4:5]
	v_cndmask_b32_e64 v12, v4, v12, s[4:5]
	v_cndmask_b32_e64 v11, v3, v11, s[4:5]
	v_cndmask_b32_e64 v10, v2, v10, s[4:5]
	s_nop 1
	v_mov_b32_dpp v24, v10 row_ror:1 row_mask:0xf bank_mask:0xf
	v_mov_b32_dpp v25, v11 row_ror:1 row_mask:0xf bank_mask:0xf
	v_mov_b32_dpp v22, v12 row_ror:1 row_mask:0xf bank_mask:0xf
	v_mov_b32_dpp v23, v13 row_ror:1 row_mask:0xf bank_mask:0xf
	v_mov_b32_dpp v26, v2 row_ror:15 row_mask:0xf bank_mask:0xf
	v_mov_b32_dpp v27, v3 row_ror:15 row_mask:0xf bank_mask:0xf
	v_mov_b32_dpp v29, v4 row_ror:15 row_mask:0xf bank_mask:0xf
	v_mov_b32_dpp v28, v5 row_ror:15 row_mask:0xf bank_mask:0xf
	v_mov_b32_e32 v10, 0
	s_and_b64 vcc, exec, s[50:51]
	v_mov_b32_e32 v11, 0
	v_mov_b32_e32 v12, 0
	v_mov_b32_e32 v13, 0
	s_cbranch_vccnz .LBB0_910
	ds_read_b128 v[10:13], v241 offset:2096
